# cross-attention QK^T: K-fragment LDS reads rotated over three register quads, two reads kept in flight with counted waits
# speedup vs baseline: 1.0025x; 1.0025x over previous
; __device__ __forceinline__ float row_rs(const float* ssq, int row) { return ssq ? rsqrtf(ssq[row] * (1.f / 1024.f) + RMS_EPS) : 1.f; }
; #define LAS __attribute__((address_space(3)))
; __device__ __forceinline__ unsigned pk2(float lo, float hi) { return pg8::cvt_pk_bf16(lo, hi); }
;     __device__ __forceinline__ void fused(f32x4 (&acc)[2][2][4][2], const pg8::Unit& u, int wr, int wc, int fr, int fq, LAS unsigned char* lds, int wid, int lane) const {
;         LAS bf16* QI = (LAS bf16*)lds;
; #pragma unroll
;         for (int ai = 0; ai < 2; ++ai)
; #pragma unroll
;             for (int m = 0; m < 4; ++m) { const int rl = ai * 128 + wr * 64 + m * 16 + fr; const float rs = pg8::row_rs(ssq, u.pm * 256 + rl);
; #pragma unroll
;                 for (int bj = 0; bj < 2; ++bj)
; #pragma unroll
;                     for (int n = 0; n < 2; ++n) { const f32x4 v = acc[ai][bj][m][n] * rs; v2u w; w.x = pk2(v[0], v[1]); w.y = pk2(v[2], v[3]);
;                         *(LAS v2u*)(QI + rl * XP + bj * 128 + wc * 32 + n * 16 + 4 * fq) = w; } }
;         __syncthreads();
.LBB0_1108:
	s_add_u32 s4, s48, 0x20000
	s_addc_u32 s5, s49, 0
	v_lshrrev_b32_e32 v128, 5, v208
	s_lshl_b32 s13, s10, 8
	v_lshlrev_b32_e32 v189, 4, v128
	v_lshlrev_b32_e32 v211, 2, v128
	v_add_u32_e32 v128, s13, v146
	v_ashrrev_i32_e32 v129, 31, v128
	v_lshl_add_u64 v[132:133], v[128:129], 2, s[4:5]
	s_barrier
	global_load_dword v131, v[132:133], off
	global_load_dword v136, v[132:133], off offset:64
	global_load_dword v137, v[132:133], off offset:128
	global_load_dword v138, v[132:133], off offset:192
	global_load_dword v139, v[132:133], off offset:512
	global_load_dword v140, v[132:133], off offset:576
	global_load_dword v141, v[132:133], off offset:640
	global_load_dword v142, v[132:133], off offset:704
	s_lshl_b32 s6, s39, 6
	v_mov_b32_e32 v129, 0x358637bd
	s_add_i32 s7, s6, 0
	s_mov_b32 s6, 0x800000
	s_movk_i32 s14, 0x210
	s_ashr_i32 s15, s10, 4
	s_add_i32 s12, 0, 0x10800
	s_andn2_b32 s30, s30, 63
	v_and_b32_e32 v210, 31, v209
	v_and_b32_e32 v188, 8, v147
	v_and_b32_e32 v190, 0x1f0, v144
	v_lshl_or_b32 v214, s31, 5, v210
	v_mov_b32_e32 v191, 0
	v_lshlrev_b32_e32 v130, 1, v188
	v_add_u32_e32 v216, 0, v190
	v_add_u32_e32 v215, s12, v190
	v_mul_u32_u24_e32 v212, 0x210, v210
	v_add3_u32 v213, 0, v212, v189
	s_mov_b32 s11, 0
	s_waitcnt vmcnt(0)
	v_fmamk_f32 v131, v131, 0x3a800000, v129
	s_nop 0
	v_rsq_f32_e32 v131, v131
	s_nop 0
	v_mov_b32_e32 v132, v131
	v_mul_lo_u32 v131, v146, s14
	v_pk_mul_f32 v[118:119], v[118:119], v[132:133] op_sel_hi:[1,0]
	v_pk_mul_f32 v[116:117], v[116:117], v[132:133] op_sel_hi:[1,0]
	v_pk_mul_f32 v[114:115], v[114:115], v[132:133] op_sel_hi:[1,0]
	v_pk_mul_f32 v[112:113], v[112:113], v[132:133] op_sel_hi:[1,0]
	v_add3_u32 v131, s7, v145, v131
	v_cvt_pk_bf16_f32 v116, v116, v117
	v_cvt_pk_bf16_f32 v117, v118, v119
	v_cvt_pk_bf16_f32 v112, v112, v113
	v_cvt_pk_bf16_f32 v113, v114, v115
	ds_write2_b64 v131, v[116:117], v[112:113] offset0:32 offset1:36
	v_pk_mul_f32 v[126:127], v[126:127], v[132:133] op_sel_hi:[1,0]
	v_pk_mul_f32 v[124:125], v[124:125], v[132:133] op_sel_hi:[1,0]
	v_pk_mul_f32 v[122:123], v[122:123], v[132:133] op_sel_hi:[1,0]
	v_pk_mul_f32 v[120:121], v[120:121], v[132:133] op_sel_hi:[1,0]
	v_cvt_pk_bf16_f32 v124, v124, v125
	v_cvt_pk_bf16_f32 v125, v126, v127
	v_cvt_pk_bf16_f32 v120, v120, v121
	v_cvt_pk_bf16_f32 v121, v122, v123
	ds_write2_b64 v131, v[124:125], v[120:121] offset1:4
	s_waitcnt vmcnt(0)
	v_fmamk_f32 v112, v136, 0x3a800000, v129
	s_nop 0
	v_rsq_f32_e32 v112, v112
	s_nop 0
	v_add_u32_e32 v113, 0x2100, v131
	v_pk_mul_f32 v[106:107], v[106:107], v[112:113] op_sel_hi:[1,0]
	v_pk_mul_f32 v[104:105], v[104:105], v[112:113] op_sel_hi:[1,0]
	v_pk_mul_f32 v[102:103], v[102:103], v[112:113] op_sel_hi:[1,0]
	v_pk_mul_f32 v[100:101], v[100:101], v[112:113] op_sel_hi:[1,0]
	v_pk_mul_f32 v[98:99], v[98:99], v[112:113] op_sel_hi:[1,0]
	v_pk_mul_f32 v[96:97], v[96:97], v[112:113] op_sel_hi:[1,0]
	v_cvt_pk_bf16_f32 v104, v104, v105
	v_cvt_pk_bf16_f32 v105, v106, v107
	v_add_u32_e32 v106, 0x2000, v131
	v_cvt_pk_bf16_f32 v100, v100, v101
	v_cvt_pk_bf16_f32 v101, v102, v103
	v_cvt_pk_bf16_f32 v96, v96, v97
	v_cvt_pk_bf16_f32 v97, v98, v99
	ds_write2_b64 v106, v[100:101], v[96:97] offset0:64 offset1:68
	v_pk_mul_f32 v[110:111], v[110:111], v[112:113] op_sel_hi:[1,0]
	v_pk_mul_f32 v[108:109], v[108:109], v[112:113] op_sel_hi:[1,0]
	s_waitcnt vmcnt(0)
	v_fmamk_f32 v96, v137, 0x3a800000, v129
	v_cvt_pk_bf16_f32 v108, v108, v109
	v_rsq_f32_e32 v96, v96
	v_cvt_pk_bf16_f32 v109, v110, v111
	ds_write2_b64 v106, v[108:109], v[104:105] offset0:32 offset1:36
	v_add_u32_e32 v97, 0x4200, v131
	v_pk_mul_f32 v[90:91], v[90:91], v[96:97] op_sel_hi:[1,0]
	v_pk_mul_f32 v[88:89], v[88:89], v[96:97] op_sel_hi:[1,0]
	v_pk_mul_f32 v[86:87], v[86:87], v[96:97] op_sel_hi:[1,0]
	v_pk_mul_f32 v[84:85], v[84:85], v[96:97] op_sel_hi:[1,0]
	v_pk_mul_f32 v[82:83], v[82:83], v[96:97] op_sel_hi:[1,0]
	v_pk_mul_f32 v[80:81], v[80:81], v[96:97] op_sel_hi:[1,0]
	v_cvt_pk_bf16_f32 v88, v88, v89
	v_cvt_pk_bf16_f32 v89, v90, v91
	v_add_u32_e32 v90, 0x4000, v131
	v_cvt_pk_bf16_f32 v84, v84, v85
	v_cvt_pk_bf16_f32 v85, v86, v87
	v_cvt_pk_bf16_f32 v80, v80, v81
	v_cvt_pk_bf16_f32 v81, v82, v83
	ds_write2_b64 v90, v[84:85], v[80:81] offset0:96 offset1:100
	v_pk_mul_f32 v[94:95], v[94:95], v[96:97] op_sel_hi:[1,0]
	v_pk_mul_f32 v[92:93], v[92:93], v[96:97] op_sel_hi:[1,0]
	s_waitcnt vmcnt(0)
	v_fmamk_f32 v80, v138, 0x3a800000, v129
	v_cvt_pk_bf16_f32 v92, v92, v93
	v_rsq_f32_e32 v80, v80
	v_cvt_pk_bf16_f32 v93, v94, v95
	ds_write2_b64 v90, v[92:93], v[88:89] offset0:64 offset1:68
	v_mov_b32_e32 v82, v80
	v_pk_mul_f32 v[74:75], v[74:75], v[82:83] op_sel_hi:[1,0]
	v_pk_mul_f32 v[72:73], v[72:73], v[82:83] op_sel_hi:[1,0]
	v_pk_mul_f32 v[70:71], v[70:71], v[82:83] op_sel_hi:[1,0]
	v_pk_mul_f32 v[68:69], v[68:69], v[82:83] op_sel_hi:[1,0]
	v_pk_mul_f32 v[66:67], v[66:67], v[82:83] op_sel_hi:[1,0]
	v_pk_mul_f32 v[64:65], v[64:65], v[82:83] op_sel_hi:[1,0]
	v_cvt_pk_bf16_f32 v72, v72, v73
	v_cvt_pk_bf16_f32 v73, v74, v75
	v_add_u32_e32 v74, 0x6000, v131
	v_cvt_pk_bf16_f32 v68, v68, v69
	v_cvt_pk_bf16_f32 v69, v70, v71
	v_cvt_pk_bf16_f32 v64, v64, v65
	v_cvt_pk_bf16_f32 v65, v66, v67
	ds_write2_b64 v74, v[68:69], v[64:65] offset0:128 offset1:132
	v_add_u32_e32 v80, 0x6300, v131
	v_pk_mul_f32 v[78:79], v[78:79], v[82:83] op_sel_hi:[1,0]
	v_pk_mul_f32 v[76:77], v[76:77], v[82:83] op_sel_hi:[1,0]
	v_add3_u32 v68, s12, v212, v189
	v_cvt_pk_bf16_f32 v76, v76, v77
	v_cvt_pk_bf16_f32 v77, v78, v79
	ds_write2_b64 v74, v[76:77], v[72:73] offset0:96 offset1:100
	v_add3_u32 v189, s12, v189, v212
	s_waitcnt vmcnt(0)
; __device__ __forceinline__ float row_rs(const float* ssq, int row) { return ssq ? rsqrtf(ssq[row] * (1.f / 1024.f) + RMS_EPS) : 1.f; }
; #define LAS __attribute__((address_space(3)))
; __device__ __forceinline__ unsigned pk2(float lo, float hi) { return pg8::cvt_pk_bf16(lo, hi); }
; __device__ __forceinline__ void xattn_core(unsigned char* ws, LAS unsigned char* lds, int b, int hd, int qb, int tid, const bf16x8 (&qf)[16]) {
;     const int lane = tid & 63, wave = tid >> 6, r32 = lane & 31, hh = lane >> 5;
;     LAS bf16* L0 = (LAS bf16*)lds; LAS bf16* L1 = L0 + 128 * XP;
;     const bf16* Kg = (const bf16*)(ws + WS_KB) + (size_t)(b * 256) * 1024 + hd * 256;
;     const bf16* Vg = (const bf16*)(ws + WS_VT) + (size_t)(hd * 256) * 1024 + b * 256;
;     stage_half(Kg, L0, tid); stage_half(Kg + (size_t)128 * 1024, L1, tid);
;     const int q0 = b * SEQ + qb * 256 + 32 * wave;
;     __device__ __forceinline__ void fused(f32x4 (&acc)[2][2][4][2], const pg8::Unit& u, int wr, int wc, int fr, int fq, LAS unsigned char* lds, int wid, int lane) const {
;     ...
;             for (int m = 0; m < 4; ++m) { const int rl = ai * 128 + wr * 64 + m * 16 + fr; const float rs = pg8::row_rs(ssq, u.pm * 256 + rl);
; #pragma unroll
;                 for (int bj = 0; bj < 2; ++bj)
; #pragma unroll
;                     for (int n = 0; n < 2; ++n) { const f32x4 v = acc[ai][bj][m][n] * rs; v2u w; w.x = pk2(v[0], v[1]); w.y = pk2(v[2], v[3]);
;                         *(LAS v2u*)(QI + rl * XP + bj * 128 + wc * 32 + n * 16 + 4 * fq) = w; } }
;         __syncthreads();
	v_fmamk_f32 v64, v139, 0x3a800000, v129
	s_nop 0
	v_rsq_f32_e32 v64, v64
	s_nop 0
	v_mov_b32_e32 v66, v64
	v_pk_mul_f32 v[54:55], v[54:55], v[66:67] op_sel_hi:[1,0]
	v_pk_mul_f32 v[52:53], v[52:53], v[66:67] op_sel_hi:[1,0]
	v_pk_mul_f32 v[50:51], v[50:51], v[66:67] op_sel_hi:[1,0]
	v_pk_mul_f32 v[48:49], v[48:49], v[66:67] op_sel_hi:[1,0]
	v_cvt_pk_bf16_f32 v52, v52, v53
	v_cvt_pk_bf16_f32 v53, v54, v55
	v_cvt_pk_bf16_f32 v48, v48, v49
	v_cvt_pk_bf16_f32 v49, v50, v51
	v_add_u32_e32 v50, 0xe800, v113
	ds_write2_b64 v50, v[52:53], v[48:49] offset1:4
	v_pk_mul_f32 v[62:63], v[62:63], v[66:67] op_sel_hi:[1,0]
	v_pk_mul_f32 v[60:61], v[60:61], v[66:67] op_sel_hi:[1,0]
	v_pk_mul_f32 v[58:59], v[58:59], v[66:67] op_sel_hi:[1,0]
	v_pk_mul_f32 v[56:57], v[56:57], v[66:67] op_sel_hi:[1,0]
	v_cvt_pk_bf16_f32 v60, v60, v61
	v_cvt_pk_bf16_f32 v61, v62, v63
	v_cvt_pk_bf16_f32 v56, v56, v57
	v_cvt_pk_bf16_f32 v57, v58, v59
	v_add_u32_e32 v58, 0xe000, v113
	ds_write2_b64 v58, v[60:61], v[56:57] offset0:224 offset1:228
	v_add_u32_e32 v64, 0xe700, v113
	s_waitcnt vmcnt(0)
	v_fmamk_f32 v48, v140, 0x3a800000, v129
	s_nop 0
	v_rsq_f32_e32 v48, v48
	s_nop 0
	v_pk_mul_f32 v[38:39], v[38:39], v[48:49] op_sel_hi:[1,0]
	v_pk_mul_f32 v[36:37], v[36:37], v[48:49] op_sel_hi:[1,0]
	v_pk_mul_f32 v[34:35], v[34:35], v[48:49] op_sel_hi:[1,0]
	v_pk_mul_f32 v[32:33], v[32:33], v[48:49] op_sel_hi:[1,0]
	v_cvt_pk_bf16_f32 v36, v36, v37
	v_cvt_pk_bf16_f32 v37, v38, v39
	v_cvt_pk_bf16_f32 v32, v32, v33
	v_cvt_pk_bf16_f32 v33, v34, v35
	v_add_u32_e32 v34, 0xe800, v97
	ds_write2_b64 v34, v[36:37], v[32:33] offset1:4
	v_pk_mul_f32 v[46:47], v[46:47], v[48:49] op_sel_hi:[1,0]
	v_pk_mul_f32 v[44:45], v[44:45], v[48:49] op_sel_hi:[1,0]
	v_pk_mul_f32 v[42:43], v[42:43], v[48:49] op_sel_hi:[1,0]
	v_pk_mul_f32 v[40:41], v[40:41], v[48:49] op_sel_hi:[1,0]
	v_cvt_pk_bf16_f32 v44, v44, v45
	v_cvt_pk_bf16_f32 v45, v46, v47
	v_cvt_pk_bf16_f32 v40, v40, v41
	v_cvt_pk_bf16_f32 v41, v42, v43
	v_add_u32_e32 v42, 0xe000, v97
	ds_write2_b64 v42, v[44:45], v[40:41] offset0:224 offset1:228
	s_waitcnt vmcnt(0)
	v_fmamk_f32 v32, v141, 0x3a800000, v129
	s_nop 0
	v_rsq_f32_e32 v32, v32
	s_nop 0
	v_pk_mul_f32 v[22:23], v[22:23], v[32:33] op_sel_hi:[1,0]
	v_pk_mul_f32 v[20:21], v[20:21], v[32:33] op_sel_hi:[1,0]
	v_pk_mul_f32 v[18:19], v[18:19], v[32:33] op_sel_hi:[1,0]
	v_pk_mul_f32 v[16:17], v[16:17], v[32:33] op_sel_hi:[1,0]
	v_cvt_pk_bf16_f32 v20, v20, v21
	v_cvt_pk_bf16_f32 v21, v22, v23
	v_cvt_pk_bf16_f32 v16, v16, v17
	v_cvt_pk_bf16_f32 v17, v18, v19
	v_add_u32_e32 v18, 0xe800, v80
	ds_write2_b64 v18, v[20:21], v[16:17] offset1:4
	v_pk_mul_f32 v[30:31], v[30:31], v[32:33] op_sel_hi:[1,0]
	v_pk_mul_f32 v[28:29], v[28:29], v[32:33] op_sel_hi:[1,0]
	v_pk_mul_f32 v[26:27], v[26:27], v[32:33] op_sel_hi:[1,0]
	v_pk_mul_f32 v[24:25], v[24:25], v[32:33] op_sel_hi:[1,0]
	v_cvt_pk_bf16_f32 v28, v28, v29
	v_cvt_pk_bf16_f32 v29, v30, v31
	v_cvt_pk_bf16_f32 v24, v24, v25
	v_cvt_pk_bf16_f32 v25, v26, v27
	v_add_u32_e32 v26, 0xe000, v80
	v_or_b32_e32 v30, s30, v208
	ds_write2_b64 v26, v[28:29], v[24:25] offset0:224 offset1:228
	v_ashrrev_i32_e32 v34, 5, v30
	v_add_u32_e32 v20, 0xa00, v30
	v_add_u32_e32 v24, 0xc00, v30
	v_ashrrev_i32_e32 v44, 5, v20
	v_ashrrev_i32_e32 v46, 5, v24
	v_ashrrev_i32_e32 v35, 31, v34
	v_ashrrev_i32_e32 v45, 31, v44
	v_ashrrev_i32_e32 v47, 31, v46
	v_lshlrev_b64 v[192:193], 11, v[34:35]
	v_lshlrev_b64 v[202:203], 11, v[44:45]
	v_lshlrev_b64 v[204:205], 11, v[46:47]
	v_mul_lo_u32 v34, v34, s14
	v_add_u32_e32 v223, v216, v34
	v_add_u32_e32 v230, v215, v34
	s_waitcnt vmcnt(0)
	v_fmac_f32_e32 v129, 0x3a800000, v142
	s_lshl_b32 s6, s15, 8
	v_rsq_f32_e32 v16, v129
	s_ashr_i32 s7, s6, 31
	s_lshl_b64 s[4:5], s[6:7], 11
	s_add_u32 s10, s48, s4
	s_addc_u32 s19, s49, s5
	s_lshl_b32 s16, s34, 8
	v_pk_mul_f32 v[14:15], v[14:15], v[16:17] op_sel_hi:[1,0]
	v_pk_mul_f32 v[12:13], v[12:13], v[16:17] op_sel_hi:[1,0]
	v_pk_mul_f32 v[10:11], v[10:11], v[16:17] op_sel_hi:[1,0]
	v_pk_mul_f32 v[8:9], v[8:9], v[16:17] op_sel_hi:[1,0]
	v_pk_mul_f32 v[6:7], v[6:7], v[16:17] op_sel_hi:[1,0]
	v_pk_mul_f32 v[4:5], v[4:5], v[16:17] op_sel_hi:[1,0]
	v_pk_mul_f32 v[2:3], v[2:3], v[16:17] op_sel_hi:[1,0]
	v_pk_mul_f32 v[0:1], v[0:1], v[16:17] op_sel_hi:[1,0]
	s_ashr_i32 s17, s16, 31
	v_cvt_pk_bf16_f32 v12, v12, v13
	v_cvt_pk_bf16_f32 v13, v14, v15
	v_cvt_pk_bf16_f32 v8, v8, v9
	v_cvt_pk_bf16_f32 v9, v10, v11
	v_add_u32_e32 v10, 0x6000, v64
	v_cvt_pk_bf16_f32 v4, v4, v5
	v_cvt_pk_bf16_f32 v5, v6, v7
	v_cvt_pk_bf16_f32 v0, v0, v1
	v_cvt_pk_bf16_f32 v1, v2, v3
	s_lshl_b64 s[4:5], s[16:17], 1
	ds_write2_b64 v10, v[12:13], v[8:9] offset0:96 offset1:100
	ds_write2_b64 v10, v[4:5], v[0:1] offset0:128 offset1:132
	s_add_u32 s18, s10, s4
	v_add_u32_e32 v4, 0x200, v30
	v_add_u32_e32 v8, 0x400, v30
	v_add_u32_e32 v12, 0x600, v30
	v_add_u32_e32 v16, 0x800, v30
	v_add_u32_e32 v30, 0xe00, v30
	s_addc_u32 s19, s19, s5
	v_ashrrev_i32_e32 v36, 5, v4
	v_ashrrev_i32_e32 v38, 5, v8
	v_ashrrev_i32_e32 v40, 5, v12
	v_ashrrev_i32_e32 v42, 5, v16
	v_ashrrev_i32_e32 v48, 5, v30
	v_mul_lo_u32 v0, v214, s14
	v_lshl_add_u64 v[32:33], s[18:19], 0, v[190:191]
	s_mov_b64 s[18:19], 0x5600000
	v_ashrrev_i32_e32 v37, 31, v36
	v_ashrrev_i32_e32 v39, 31, v38
	v_ashrrev_i32_e32 v41, 31, v40
	v_ashrrev_i32_e32 v43, 31, v42
	v_ashrrev_i32_e32 v49, 31, v48
	v_add3_u32 v0, 0, v130, v0
	v_lshl_add_u64 v[28:29], v[32:33], 0, s[18:19]
	v_lshlrev_b64 v[194:195], 11, v[36:37]
	v_lshlrev_b64 v[196:197], 11, v[38:39]
	v_lshlrev_b64 v[198:199], 11, v[40:41]
	v_lshlrev_b64 v[200:201], 11, v[42:43]
	v_lshlrev_b64 v[206:207], 11, v[48:49]
	s_waitcnt lgkmcnt(0)
	s_barrier
; #define LAS __attribute__((address_space(3)))
; __device__ __forceinline__ void stage_half(const bf16* g, LAS bf16* dst, int tid) {
;     v4u t[8];
; #pragma unroll
;     for (int i = 0; i < 8; ++i) { const int ch = tid + i * NT, r = ch >> 5, cc = ch & 31; t[i] = *(const v4u*)(g + (size_t)r * 1024 + cc * 8); }
; #pragma unroll
;     for (int i = 0; i < 8; ++i) { const int ch = tid + i * NT, r = ch >> 5, cc = ch & 31; *(LAS v4u*)(dst + r * XP + cc * 8) = t[i]; }
; }
; __device__ __forceinline__ void xattn_core(unsigned char* ws, LAS unsigned char* lds, int b, int hd, int qb, int tid, const bf16x8 (&qf)[16]) {
;     const int lane = tid & 63, wave = tid >> 6, r32 = lane & 31, hh = lane >> 5;
;     LAS bf16* L0 = (LAS bf16*)lds; LAS bf16* L1 = L0 + 128 * XP;
;     const bf16* Kg = (const bf16*)(ws + WS_KB) + (size_t)(b * 256) * 1024 + hd * 256;
;     const bf16* Vg = (const bf16*)(ws + WS_VT) + (size_t)(hd * 256) * 1024 + b * 256;
;     stage_half(Kg, L0, tid); stage_half(Kg + (size_t)128 * 1024, L1, tid);
;     const int q0 = b * SEQ + qb * 256 + 32 * wave;
;     __syncthreads();
;     f32x16 sacc[8];
; #pragma unroll
;     for (int mt = 0; mt < 8; ++mt) {
; #pragma unroll
;         for (int r = 0; r < 16; ++r) sacc[mt][r] = 0.f;
;         const LAS bf16* kp = (mt < 4 ? L0 : L1) + ((mt & 3) * 32 + r32) * XP + 8 * hh;
; #pragma unroll
;         for (int ds = 0; ds < 16; ++ds) { const bf16x8 kf = *(const LAS bf16x8*)(kp + 16 * ds); sacc[mt] = __builtin_amdgcn_mfma_f32_32x32x16_bf16(kf, qf[ds], sacc[mt], 0, 0, 0); } }
;     __device__ __forceinline__ void fused(f32x4 (&acc)[2][2][4][2], const pg8::Unit& u, int wr, int wc, int fr, int fq, LAS unsigned char* lds, int wid, int lane) const {
;     ...
;         const int r32 = lane & 31, hh = lane >> 5; bf16x8 qf[16];
; #pragma unroll
;         for (int ds = 0; ds < 16; ++ds) qf[ds] = *(const LAS bf16x8*)(QI + (32 * wid + r32) * XP + 16 * ds + 8 * hh);
;         __syncthreads();
	ds_read_b128 v[112:115], v0
	ds_read_b128 v[184:187], v0 offset:32
	ds_read_b128 v[180:183], v0 offset:64
	ds_read_b128 v[176:179], v0 offset:96
	ds_read_b128 v[172:175], v0 offset:128
	ds_read_b128 v[168:171], v0 offset:160
	ds_read_b128 v[164:167], v0 offset:192
	ds_read_b128 v[160:163], v0 offset:224
	ds_read_b128 v[156:159], v0 offset:256
	ds_read_b128 v[152:155], v0 offset:288
	ds_read_b128 v[148:151], v0 offset:320
	ds_read_b128 v[144:147], v0 offset:352
	ds_read_b128 v[140:143], v0 offset:384
	ds_read_b128 v[136:139], v0 offset:416
	ds_read_b128 v[132:135], v0 offset:448
	ds_read_b128 v[128:131], v0 offset:480
	v_lshl_add_u64 v[0:1], v[28:29], 0, v[192:193]
	v_lshl_add_u64 v[4:5], v[28:29], 0, v[194:195]
	v_lshl_add_u64 v[8:9], v[28:29], 0, v[196:197]
	v_lshl_add_u64 v[12:13], v[28:29], 0, v[198:199]
	v_lshl_add_u64 v[16:17], v[28:29], 0, v[200:201]
	v_lshl_add_u64 v[20:21], v[28:29], 0, v[202:203]
	v_lshl_add_u64 v[24:25], v[28:29], 0, v[204:205]
	v_lshl_add_u64 v[28:29], v[28:29], 0, v[206:207]
	s_waitcnt lgkmcnt(0)
	s_barrier
	s_mov_b64 s[18:19], 0x5640000
	v_lshl_add_u64 v[100:101], v[32:33], 0, s[18:19]
	v_lshl_add_u64 v[72:73], v[100:101], 0, v[192:193]
	v_lshl_add_u64 v[76:77], v[100:101], 0, v[194:195]
	v_lshl_add_u64 v[80:81], v[100:101], 0, v[196:197]
	v_lshl_add_u64 v[84:85], v[100:101], 0, v[198:199]
	v_lshl_add_u64 v[88:89], v[100:101], 0, v[200:201]
	v_lshl_add_u64 v[92:93], v[100:101], 0, v[202:203]
	v_lshl_add_u64 v[96:97], v[100:101], 0, v[204:205]
	v_lshl_add_u64 v[100:101], v[100:101], 0, v[206:207]
	global_load_dwordx4 v[0:3], v[0:1], off
	v_mul_lo_u32 v35, v36, s14
	global_load_dwordx4 v[4:7], v[4:5], off
	v_mul_lo_u32 v36, v38, s14
	global_load_dwordx4 v[8:11], v[8:9], off
	v_mul_lo_u32 v37, v40, s14
	global_load_dwordx4 v[12:15], v[12:13], off
	v_mul_lo_u32 v38, v42, s14
	global_load_dwordx4 v[16:19], v[16:17], off
	v_mul_lo_u32 v39, v44, s14
	global_load_dwordx4 v[20:23], v[20:21], off
	v_mul_lo_u32 v40, v46, s14
	global_load_dwordx4 v[24:27], v[24:25], off
	v_mul_lo_u32 v41, v48, s14
	global_load_dwordx4 v[28:31], v[28:29], off
	global_load_dwordx4 v[72:75], v[72:73], off
	global_load_dwordx4 v[76:79], v[76:77], off
	global_load_dwordx4 v[80:83], v[80:81], off
	global_load_dwordx4 v[84:87], v[84:85], off
	global_load_dwordx4 v[88:91], v[88:89], off
	global_load_dwordx4 v[92:95], v[92:93], off
	global_load_dwordx4 v[96:99], v[96:97], off
	global_load_dwordx4 v[100:103], v[100:101], off
	v_add_u32_e32 v222, v216, v35
	v_add_u32_e32 v221, v216, v36
	v_add_u32_e32 v220, v216, v37
	v_add_u32_e32 v219, v216, v38
	v_add_u32_e32 v218, v216, v39
	v_add_u32_e32 v217, v216, v40
	v_add_u32_e32 v216, v216, v41
	s_mov_b64 s[18:19], 0x5640000
	v_add_u32_e32 v224, v215, v35
	v_add_u32_e32 v225, v215, v36
	v_add_u32_e32 v226, v215, v37
	v_add_u32_e32 v227, v215, v38
	v_add_u32_e32 v228, v215, v39
	v_add_u32_e32 v229, v215, v40
	v_add_u32_e32 v215, v215, v41
	s_lshl_b64 s[16:17], s[16:17], 11
	s_add_u32 s16, s48, s16
	s_addc_u32 s17, s49, s17
	s_and_b32 s10, s13, 0xf00
	s_lshl_b64 s[6:7], s[6:7], 1
	s_add_u32 s16, s16, s6
	s_addc_u32 s17, s17, s7
	s_lshl_b32 s6, s15, 12
	s_mov_b64 s[14:15], 0x5800000
	s_mov_b32 s7, 0xff61b1e6
	s_or_b32 s6, s10, s6
	s_waitcnt vmcnt(15)
	ds_write_b128 v223, v[0:3]
	s_waitcnt vmcnt(14)
	ds_write_b128 v222, v[4:7]
	s_waitcnt vmcnt(13)
	ds_write_b128 v221, v[8:11]
	s_waitcnt vmcnt(12)
	ds_write_b128 v220, v[12:15]
	s_waitcnt vmcnt(11)
	ds_write_b128 v219, v[16:19]
	s_waitcnt vmcnt(10)
	ds_write_b128 v218, v[20:23]
	s_waitcnt vmcnt(9)
	ds_write_b128 v217, v[24:27]
	s_waitcnt vmcnt(8)
	ds_write_b128 v216, v[28:31]
	s_waitcnt vmcnt(7)
	ds_write_b128 v230, v[72:75]
	s_waitcnt vmcnt(6)
	ds_write_b128 v224, v[76:79]
	s_waitcnt vmcnt(5)
	ds_write_b128 v225, v[80:83]
	s_waitcnt vmcnt(4)
	ds_write_b128 v226, v[84:87]
	s_waitcnt vmcnt(3)
	ds_write_b128 v227, v[88:91]
	s_waitcnt vmcnt(2)
	ds_write_b128 v228, v[92:95]
	s_waitcnt vmcnt(1)
	ds_write_b128 v229, v[96:99]
	s_waitcnt vmcnt(0)
	ds_write_b128 v215, v[100:103]
	s_waitcnt lgkmcnt(0)
	s_barrier
	ds_read_b128 v[236:239], v213
	ds_read_b128 v[240:243], v213 offset:32
	ds_read_b128 v[244:247], v213 offset:64
	s_waitcnt lgkmcnt(2)
	v_mfma_f32_32x32x16_bf16 v[96:111], v[236:239], v[112:115], 0
	ds_read_b128 v[236:239], v213 offset:96
	s_waitcnt lgkmcnt(2)
	v_mfma_f32_32x32x16_bf16 v[96:111], v[240:243], v[184:187], v[96:111]
	ds_read_b128 v[240:243], v213 offset:128
	s_waitcnt lgkmcnt(2)
	v_mfma_f32_32x32x16_bf16 v[96:111], v[244:247], v[180:183], v[96:111]
	ds_read_b128 v[244:247], v213 offset:160
	s_waitcnt lgkmcnt(2)
	v_mfma_f32_32x32x16_bf16 v[96:111], v[236:239], v[176:179], v[96:111]
	ds_read_b128 v[236:239], v213 offset:192
	s_waitcnt lgkmcnt(2)
	v_mfma_f32_32x32x16_bf16 v[96:111], v[240:243], v[172:175], v[96:111]
	ds_read_b128 v[240:243], v213 offset:224
	s_waitcnt lgkmcnt(2)
	v_mfma_f32_32x32x16_bf16 v[96:111], v[244:247], v[168:171], v[96:111]
	ds_read_b128 v[244:247], v213 offset:256
	s_waitcnt lgkmcnt(2)
	v_mfma_f32_32x32x16_bf16 v[96:111], v[236:239], v[164:167], v[96:111]
	ds_read_b128 v[236:239], v213 offset:288
	s_waitcnt lgkmcnt(2)
	v_mfma_f32_32x32x16_bf16 v[96:111], v[240:243], v[160:163], v[96:111]
	ds_read_b128 v[240:243], v213 offset:320
	s_waitcnt lgkmcnt(2)
	v_mfma_f32_32x32x16_bf16 v[96:111], v[244:247], v[156:159], v[96:111]
	ds_read_b128 v[244:247], v213 offset:352
	s_waitcnt lgkmcnt(2)
	v_mfma_f32_32x32x16_bf16 v[96:111], v[236:239], v[152:155], v[96:111]
	ds_read_b128 v[236:239], v213 offset:384
	s_waitcnt lgkmcnt(2)
	v_mfma_f32_32x32x16_bf16 v[96:111], v[240:243], v[148:151], v[96:111]
	ds_read_b128 v[240:243], v213 offset:416
	s_waitcnt lgkmcnt(2)
; #define LAS __attribute__((address_space(3)))
; __device__ __forceinline__ void xattn_core(unsigned char* ws, LAS unsigned char* lds, int b, int hd, int qb, int tid, const bf16x8 (&qf)[16]) {
;     ...
;     for (int mt = 0; mt < 8; ++mt) {
; #pragma unroll
;         for (int r = 0; r < 16; ++r) sacc[mt][r] = 0.f;
;         const LAS bf16* kp = (mt < 4 ? L0 : L1) + ((mt & 3) * 32 + r32) * XP + 8 * hh;
; #pragma unroll
;         for (int ds = 0; ds < 16; ++ds) { const bf16x8 kf = *(const LAS bf16x8*)(kp + 16 * ds); sacc[mt] = __builtin_amdgcn_mfma_f32_32x32x16_bf16(kf, qf[ds], sacc[mt], 0, 0, 0); } }
	v_mfma_f32_32x32x16_bf16 v[96:111], v[244:247], v[144:147], v[96:111]
	ds_read_b128 v[244:247], v213 offset:448
	s_waitcnt lgkmcnt(2)
	v_mfma_f32_32x32x16_bf16 v[96:111], v[236:239], v[140:143], v[96:111]
	ds_read_b128 v[236:239], v213 offset:480
	s_waitcnt lgkmcnt(2)
	v_mfma_f32_32x32x16_bf16 v[96:111], v[240:243], v[136:139], v[96:111]
	ds_read_b128 v[240:243], v213 offset:16896
	s_waitcnt lgkmcnt(2)
	v_mfma_f32_32x32x16_bf16 v[96:111], v[244:247], v[132:135], v[96:111]
	ds_read_b128 v[244:247], v213 offset:16928
	s_waitcnt lgkmcnt(2)
	v_mfma_f32_32x32x16_bf16 v[96:111], v[236:239], v[128:131], v[96:111]
	ds_read_b128 v[236:239], v213 offset:16960
	s_waitcnt lgkmcnt(2)
	v_mfma_f32_32x32x16_bf16 v[32:47], v[240:243], v[112:115], 0
	ds_read_b128 v[240:243], v213 offset:16992
	s_waitcnt lgkmcnt(2)
	v_mfma_f32_32x32x16_bf16 v[32:47], v[244:247], v[184:187], v[32:47]
	ds_read_b128 v[244:247], v213 offset:17024
	s_waitcnt lgkmcnt(2)
	v_mfma_f32_32x32x16_bf16 v[32:47], v[236:239], v[180:183], v[32:47]
	ds_read_b128 v[236:239], v213 offset:17056
	s_waitcnt lgkmcnt(2)
	v_mfma_f32_32x32x16_bf16 v[32:47], v[240:243], v[176:179], v[32:47]
	ds_read_b128 v[240:243], v213 offset:17088
	s_waitcnt lgkmcnt(2)
	v_mfma_f32_32x32x16_bf16 v[32:47], v[244:247], v[172:175], v[32:47]
	ds_read_b128 v[244:247], v213 offset:17120
	s_waitcnt lgkmcnt(2)
	v_mfma_f32_32x32x16_bf16 v[32:47], v[236:239], v[168:171], v[32:47]
	ds_read_b128 v[236:239], v213 offset:17152
	s_waitcnt lgkmcnt(2)
	v_mfma_f32_32x32x16_bf16 v[32:47], v[240:243], v[164:167], v[32:47]
	ds_read_b128 v[240:243], v213 offset:17184
	s_waitcnt lgkmcnt(2)
	v_mfma_f32_32x32x16_bf16 v[32:47], v[244:247], v[160:163], v[32:47]
	ds_read_b128 v[244:247], v213 offset:17216
	s_waitcnt lgkmcnt(2)
	v_mfma_f32_32x32x16_bf16 v[32:47], v[236:239], v[156:159], v[32:47]
	ds_read_b128 v[236:239], v213 offset:17248
	s_waitcnt lgkmcnt(2)
	v_mfma_f32_32x32x16_bf16 v[32:47], v[240:243], v[152:155], v[32:47]
	ds_read_b128 v[240:243], v213 offset:17280
	s_waitcnt lgkmcnt(2)
	v_mfma_f32_32x32x16_bf16 v[32:47], v[244:247], v[148:151], v[32:47]
	ds_read_b128 v[244:247], v213 offset:17312
	s_waitcnt lgkmcnt(2)
	v_mfma_f32_32x32x16_bf16 v[32:47], v[236:239], v[144:147], v[32:47]
	ds_read_b128 v[236:239], v213 offset:17344
	s_waitcnt lgkmcnt(2)
	v_mfma_f32_32x32x16_bf16 v[32:47], v[240:243], v[140:143], v[32:47]
	ds_read_b128 v[240:243], v213 offset:17376
	s_waitcnt lgkmcnt(2)
	v_mfma_f32_32x32x16_bf16 v[32:47], v[244:247], v[136:139], v[32:47]
	ds_read_b128 v[244:247], v213 offset:33792
	s_waitcnt lgkmcnt(2)
	v_mfma_f32_32x32x16_bf16 v[32:47], v[236:239], v[132:135], v[32:47]
	ds_read_b128 v[236:239], v213 offset:33824
	s_waitcnt lgkmcnt(2)
	v_mfma_f32_32x32x16_bf16 v[32:47], v[240:243], v[128:131], v[32:47]
	ds_read_b128 v[240:243], v213 offset:33856
	s_waitcnt lgkmcnt(2)
	v_mfma_f32_32x32x16_bf16 v[16:31], v[244:247], v[112:115], 0
	ds_read_b128 v[244:247], v213 offset:33888
	s_waitcnt lgkmcnt(2)
	v_mfma_f32_32x32x16_bf16 v[16:31], v[236:239], v[184:187], v[16:31]
	ds_read_b128 v[236:239], v213 offset:33920
	s_waitcnt lgkmcnt(2)
	v_mfma_f32_32x32x16_bf16 v[16:31], v[240:243], v[180:183], v[16:31]
	ds_read_b128 v[240:243], v213 offset:33952
	s_waitcnt lgkmcnt(2)
	v_mfma_f32_32x32x16_bf16 v[16:31], v[244:247], v[176:179], v[16:31]
	ds_read_b128 v[244:247], v213 offset:33984
	s_waitcnt lgkmcnt(2)
	v_mfma_f32_32x32x16_bf16 v[16:31], v[236:239], v[172:175], v[16:31]
	ds_read_b128 v[236:239], v213 offset:34016
	s_waitcnt lgkmcnt(2)
	v_mfma_f32_32x32x16_bf16 v[16:31], v[240:243], v[168:171], v[16:31]
	ds_read_b128 v[240:243], v213 offset:34048
	s_waitcnt lgkmcnt(2)
	v_mfma_f32_32x32x16_bf16 v[16:31], v[244:247], v[164:167], v[16:31]
	ds_read_b128 v[244:247], v213 offset:34080
	s_waitcnt lgkmcnt(2)
	v_mfma_f32_32x32x16_bf16 v[16:31], v[236:239], v[160:163], v[16:31]
	ds_read_b128 v[236:239], v213 offset:34112
	s_waitcnt lgkmcnt(2)
	v_mfma_f32_32x32x16_bf16 v[16:31], v[240:243], v[156:159], v[16:31]
	ds_read_b128 v[240:243], v213 offset:34144
	s_waitcnt lgkmcnt(2)
	v_mfma_f32_32x32x16_bf16 v[16:31], v[244:247], v[152:155], v[16:31]
	ds_read_b128 v[244:247], v213 offset:34176
	s_waitcnt lgkmcnt(2)
	v_mfma_f32_32x32x16_bf16 v[16:31], v[236:239], v[148:151], v[16:31]
	ds_read_b128 v[236:239], v213 offset:34208
	s_waitcnt lgkmcnt(2)
	v_mfma_f32_32x32x16_bf16 v[16:31], v[240:243], v[144:147], v[16:31]
	ds_read_b128 v[240:243], v213 offset:34240
	s_waitcnt lgkmcnt(2)
	v_mfma_f32_32x32x16_bf16 v[16:31], v[244:247], v[140:143], v[16:31]
	ds_read_b128 v[244:247], v213 offset:34272
	s_waitcnt lgkmcnt(2)
	v_mfma_f32_32x32x16_bf16 v[16:31], v[236:239], v[136:139], v[16:31]
	ds_read_b128 v[236:239], v213 offset:50688
	s_waitcnt lgkmcnt(2)
	v_mfma_f32_32x32x16_bf16 v[16:31], v[240:243], v[132:135], v[16:31]
	ds_read_b128 v[240:243], v213 offset:50720
	s_waitcnt lgkmcnt(2)
	v_mfma_f32_32x32x16_bf16 v[16:31], v[244:247], v[128:131], v[16:31]
	ds_read_b128 v[244:247], v213 offset:50752
	s_waitcnt lgkmcnt(2)
	v_mfma_f32_32x32x16_bf16 v[0:15], v[236:239], v[112:115], 0
	ds_read_b128 v[236:239], v213 offset:50784
	s_waitcnt lgkmcnt(2)
	v_mfma_f32_32x32x16_bf16 v[0:15], v[240:243], v[184:187], v[0:15]
	ds_read_b128 v[240:243], v213 offset:50816
	s_waitcnt lgkmcnt(2)
	v_mfma_f32_32x32x16_bf16 v[0:15], v[244:247], v[180:183], v[0:15]
	ds_read_b128 v[244:247], v213 offset:50848
	s_waitcnt lgkmcnt(2)
	v_mfma_f32_32x32x16_bf16 v[0:15], v[236:239], v[176:179], v[0:15]
	ds_read_b128 v[236:239], v213 offset:50880
	s_waitcnt lgkmcnt(2)
	v_mfma_f32_32x32x16_bf16 v[0:15], v[240:243], v[172:175], v[0:15]
	ds_read_b128 v[240:243], v213 offset:50912
	s_waitcnt lgkmcnt(2)
; #define LAS __attribute__((address_space(3)))
; __device__ __forceinline__ void xattn_core(unsigned char* ws, LAS unsigned char* lds, int b, int hd, int qb, int tid, const bf16x8 (&qf)[16]) {
;     ...
;     for (int mt = 0; mt < 8; ++mt) {
; #pragma unroll
;         for (int r = 0; r < 16; ++r) sacc[mt][r] = 0.f;
;         const LAS bf16* kp = (mt < 4 ? L0 : L1) + ((mt & 3) * 32 + r32) * XP + 8 * hh;
; #pragma unroll
;         for (int ds = 0; ds < 16; ++ds) { const bf16x8 kf = *(const LAS bf16x8*)(kp + 16 * ds); sacc[mt] = __builtin_amdgcn_mfma_f32_32x32x16_bf16(kf, qf[ds], sacc[mt], 0, 0, 0); } }
	v_mfma_f32_32x32x16_bf16 v[0:15], v[244:247], v[168:171], v[0:15]
	ds_read_b128 v[244:247], v213 offset:50944
	s_waitcnt lgkmcnt(2)
	v_mfma_f32_32x32x16_bf16 v[0:15], v[236:239], v[164:167], v[0:15]
	ds_read_b128 v[236:239], v213 offset:50976
	s_waitcnt lgkmcnt(2)
	v_mfma_f32_32x32x16_bf16 v[0:15], v[240:243], v[160:163], v[0:15]
	ds_read_b128 v[240:243], v213 offset:51008
	s_waitcnt lgkmcnt(2)
	v_mfma_f32_32x32x16_bf16 v[0:15], v[244:247], v[156:159], v[0:15]
	ds_read_b128 v[244:247], v213 offset:51040
	s_waitcnt lgkmcnt(2)
	v_mfma_f32_32x32x16_bf16 v[0:15], v[236:239], v[152:155], v[0:15]
	ds_read_b128 v[236:239], v213 offset:51072
	s_waitcnt lgkmcnt(2)
	v_mfma_f32_32x32x16_bf16 v[0:15], v[240:243], v[148:151], v[0:15]
	ds_read_b128 v[240:243], v213 offset:51104
	s_waitcnt lgkmcnt(2)
	v_mfma_f32_32x32x16_bf16 v[0:15], v[244:247], v[144:147], v[0:15]
	ds_read_b128 v[244:247], v213 offset:51136
	s_waitcnt lgkmcnt(2)
	v_mfma_f32_32x32x16_bf16 v[0:15], v[236:239], v[140:143], v[0:15]
	ds_read_b128 v[236:239], v213 offset:51168
	s_waitcnt lgkmcnt(2)
	v_mfma_f32_32x32x16_bf16 v[0:15], v[240:243], v[136:139], v[0:15]
	ds_read_b128 v[240:243], v68
	s_waitcnt lgkmcnt(2)
	v_mfma_f32_32x32x16_bf16 v[0:15], v[244:247], v[132:135], v[0:15]
	ds_read_b128 v[244:247], v68 offset:32
	s_waitcnt lgkmcnt(2)
	v_mfma_f32_32x32x16_bf16 v[0:15], v[236:239], v[128:131], v[0:15]
	ds_read_b128 v[236:239], v68 offset:64
	s_waitcnt lgkmcnt(2)
	v_mfma_f32_32x32x16_bf16 v[48:63], v[240:243], v[112:115], 0
	ds_read_b128 v[240:243], v68 offset:96
	s_waitcnt lgkmcnt(2)
	v_mfma_f32_32x32x16_bf16 v[48:63], v[244:247], v[184:187], v[48:63]
	ds_read_b128 v[244:247], v68 offset:128
	s_waitcnt lgkmcnt(2)
	v_mfma_f32_32x32x16_bf16 v[48:63], v[236:239], v[180:183], v[48:63]
	ds_read_b128 v[236:239], v68 offset:160
	s_waitcnt lgkmcnt(2)
	v_mfma_f32_32x32x16_bf16 v[48:63], v[240:243], v[176:179], v[48:63]
	ds_read_b128 v[240:243], v68 offset:192
	s_waitcnt lgkmcnt(2)
	v_mfma_f32_32x32x16_bf16 v[48:63], v[244:247], v[172:175], v[48:63]
	ds_read_b128 v[244:247], v68 offset:224
	s_waitcnt lgkmcnt(2)
	v_mfma_f32_32x32x16_bf16 v[48:63], v[236:239], v[168:171], v[48:63]
	ds_read_b128 v[236:239], v68 offset:256
	s_waitcnt lgkmcnt(2)
	v_mfma_f32_32x32x16_bf16 v[48:63], v[240:243], v[164:167], v[48:63]
	ds_read_b128 v[240:243], v68 offset:288
	s_waitcnt lgkmcnt(2)
	v_mfma_f32_32x32x16_bf16 v[48:63], v[244:247], v[160:163], v[48:63]
	ds_read_b128 v[244:247], v68 offset:320
	s_waitcnt lgkmcnt(2)
	v_mfma_f32_32x32x16_bf16 v[48:63], v[236:239], v[156:159], v[48:63]
	ds_read_b128 v[236:239], v68 offset:352
	s_waitcnt lgkmcnt(2)
	v_mfma_f32_32x32x16_bf16 v[48:63], v[240:243], v[152:155], v[48:63]
	ds_read_b128 v[240:243], v68 offset:384
	s_waitcnt lgkmcnt(2)
	v_mfma_f32_32x32x16_bf16 v[48:63], v[244:247], v[148:151], v[48:63]
	ds_read_b128 v[244:247], v68 offset:416
	s_waitcnt lgkmcnt(2)
	v_mfma_f32_32x32x16_bf16 v[48:63], v[236:239], v[144:147], v[48:63]
	ds_read_b128 v[236:239], v68 offset:448
	s_waitcnt lgkmcnt(2)
	v_mfma_f32_32x32x16_bf16 v[48:63], v[240:243], v[140:143], v[48:63]
	ds_read_b128 v[240:243], v68 offset:480
	s_waitcnt lgkmcnt(2)
	v_mfma_f32_32x32x16_bf16 v[48:63], v[244:247], v[136:139], v[48:63]
	ds_read_b128 v[244:247], v189 offset:16896
	s_waitcnt lgkmcnt(2)
	v_mfma_f32_32x32x16_bf16 v[48:63], v[236:239], v[132:135], v[48:63]
	ds_read_b128 v[236:239], v189 offset:16928
	s_waitcnt lgkmcnt(2)
	v_mfma_f32_32x32x16_bf16 v[48:63], v[240:243], v[128:131], v[48:63]
	ds_read_b128 v[240:243], v189 offset:16960
	s_waitcnt lgkmcnt(2)
	v_mfma_f32_32x32x16_bf16 v[80:95], v[244:247], v[112:115], 0
	ds_read_b128 v[244:247], v189 offset:16992
	s_waitcnt lgkmcnt(2)
	v_mfma_f32_32x32x16_bf16 v[80:95], v[236:239], v[184:187], v[80:95]
	ds_read_b128 v[236:239], v189 offset:17024
	s_waitcnt lgkmcnt(2)
	v_mfma_f32_32x32x16_bf16 v[80:95], v[240:243], v[180:183], v[80:95]
	ds_read_b128 v[240:243], v189 offset:17056
	s_waitcnt lgkmcnt(2)
	v_mfma_f32_32x32x16_bf16 v[80:95], v[244:247], v[176:179], v[80:95]
	ds_read_b128 v[244:247], v189 offset:17088
	s_waitcnt lgkmcnt(2)
	v_mfma_f32_32x32x16_bf16 v[80:95], v[236:239], v[172:175], v[80:95]
	ds_read_b128 v[236:239], v189 offset:17120
	s_waitcnt lgkmcnt(2)
	v_mfma_f32_32x32x16_bf16 v[80:95], v[240:243], v[168:171], v[80:95]
	ds_read_b128 v[240:243], v189 offset:17152
	s_waitcnt lgkmcnt(2)
	v_mfma_f32_32x32x16_bf16 v[80:95], v[244:247], v[164:167], v[80:95]
	ds_read_b128 v[244:247], v189 offset:17184
	s_waitcnt lgkmcnt(2)
	v_mfma_f32_32x32x16_bf16 v[80:95], v[236:239], v[160:163], v[80:95]
	ds_read_b128 v[236:239], v189 offset:17216
	s_waitcnt lgkmcnt(2)
	v_mfma_f32_32x32x16_bf16 v[80:95], v[240:243], v[156:159], v[80:95]
	ds_read_b128 v[240:243], v189 offset:17248
	s_waitcnt lgkmcnt(2)
	v_mfma_f32_32x32x16_bf16 v[80:95], v[244:247], v[152:155], v[80:95]
	ds_read_b128 v[244:247], v189 offset:17280
	s_waitcnt lgkmcnt(2)
	v_mfma_f32_32x32x16_bf16 v[80:95], v[236:239], v[148:151], v[80:95]
	ds_read_b128 v[236:239], v189 offset:17312
	s_waitcnt lgkmcnt(2)
	v_mfma_f32_32x32x16_bf16 v[80:95], v[240:243], v[144:147], v[80:95]
	ds_read_b128 v[240:243], v189 offset:17344
	s_waitcnt lgkmcnt(2)
	v_mfma_f32_32x32x16_bf16 v[80:95], v[244:247], v[140:143], v[80:95]
	ds_read_b128 v[244:247], v189 offset:17376
	s_waitcnt lgkmcnt(2)
	v_mfma_f32_32x32x16_bf16 v[80:95], v[236:239], v[136:139], v[80:95]
	ds_read_b128 v[236:239], v189 offset:33792
	s_waitcnt lgkmcnt(2)
	v_mfma_f32_32x32x16_bf16 v[80:95], v[240:243], v[132:135], v[80:95]
	ds_read_b128 v[240:243], v189 offset:33824
	s_waitcnt lgkmcnt(2)
	v_mfma_f32_32x32x16_bf16 v[80:95], v[244:247], v[128:131], v[80:95]
	ds_read_b128 v[244:247], v189 offset:33856
	s_waitcnt lgkmcnt(2)
; #define LAS __attribute__((address_space(3)))
; __device__ __forceinline__ void stage_half(const bf16* g, LAS bf16* dst, int tid) {
;     v4u t[8];
; #pragma unroll
;     for (int i = 0; i < 8; ++i) { const int ch = tid + i * NT, r = ch >> 5, cc = ch & 31; t[i] = *(const v4u*)(g + (size_t)r * 1024 + cc * 8); }
; #pragma unroll
;     for (int i = 0; i < 8; ++i) { const int ch = tid + i * NT, r = ch >> 5, cc = ch & 31; *(LAS v4u*)(dst + r * XP + cc * 8) = t[i]; }
; }
; __device__ __forceinline__ void xattn_core(unsigned char* ws, LAS unsigned char* lds, int b, int hd, int qb, int tid, const bf16x8 (&qf)[16]) {
;     ...
;     for (int mt = 0; mt < 8; ++mt) {
; #pragma unroll
;         for (int r = 0; r < 16; ++r) sacc[mt][r] = 0.f;
;         const LAS bf16* kp = (mt < 4 ? L0 : L1) + ((mt & 3) * 32 + r32) * XP + 8 * hh;
; #pragma unroll
;         for (int ds = 0; ds < 16; ++ds) { const bf16x8 kf = *(const LAS bf16x8*)(kp + 16 * ds); sacc[mt] = __builtin_amdgcn_mfma_f32_32x32x16_bf16(kf, qf[ds], sacc[mt], 0, 0, 0); } }
;     __syncthreads();
;     stage_half(Vg, L0, tid); stage_half(Vg + (size_t)128 * 1024, L1, tid);
	v_mfma_f32_32x32x16_bf16 v[64:79], v[236:239], v[112:115], 0
	ds_read_b128 v[236:239], v189 offset:33888
	s_waitcnt lgkmcnt(2)
	v_mfma_f32_32x32x16_bf16 v[64:79], v[240:243], v[184:187], v[64:79]
	ds_read_b128 v[240:243], v189 offset:33920
	s_waitcnt lgkmcnt(2)
	v_mfma_f32_32x32x16_bf16 v[64:79], v[244:247], v[180:183], v[64:79]
	ds_read_b128 v[244:247], v189 offset:33952
	s_waitcnt lgkmcnt(2)
	v_mfma_f32_32x32x16_bf16 v[64:79], v[236:239], v[176:179], v[64:79]
	ds_read_b128 v[236:239], v189 offset:33984
	s_waitcnt lgkmcnt(2)
	v_mfma_f32_32x32x16_bf16 v[64:79], v[240:243], v[172:175], v[64:79]
	ds_read_b128 v[240:243], v189 offset:34016
	s_waitcnt lgkmcnt(2)
	v_mfma_f32_32x32x16_bf16 v[64:79], v[244:247], v[168:171], v[64:79]
	ds_read_b128 v[244:247], v189 offset:34048
	s_waitcnt lgkmcnt(2)
	v_mfma_f32_32x32x16_bf16 v[64:79], v[236:239], v[164:167], v[64:79]
	ds_read_b128 v[236:239], v189 offset:34080
	s_waitcnt lgkmcnt(2)
	v_mfma_f32_32x32x16_bf16 v[64:79], v[240:243], v[160:163], v[64:79]
	ds_read_b128 v[240:243], v189 offset:34112
	s_waitcnt lgkmcnt(2)
	v_mfma_f32_32x32x16_bf16 v[64:79], v[244:247], v[156:159], v[64:79]
	ds_read_b128 v[244:247], v189 offset:34144
	s_waitcnt lgkmcnt(2)
	v_mfma_f32_32x32x16_bf16 v[64:79], v[236:239], v[152:155], v[64:79]
	ds_read_b128 v[236:239], v189 offset:34176
	s_waitcnt lgkmcnt(2)
	v_mfma_f32_32x32x16_bf16 v[64:79], v[240:243], v[148:151], v[64:79]
	ds_read_b128 v[240:243], v189 offset:34208
	s_waitcnt lgkmcnt(2)
	v_mfma_f32_32x32x16_bf16 v[64:79], v[244:247], v[144:147], v[64:79]
	ds_read_b128 v[244:247], v189 offset:34240
	s_waitcnt lgkmcnt(2)
	v_mfma_f32_32x32x16_bf16 v[64:79], v[236:239], v[140:143], v[64:79]
	ds_read_b128 v[236:239], v189 offset:34272
	s_waitcnt lgkmcnt(2)
	v_mfma_f32_32x32x16_bf16 v[64:79], v[240:243], v[136:139], v[64:79]
	ds_read_b128 v[240:243], v189 offset:50688
	s_waitcnt lgkmcnt(2)
	v_mfma_f32_32x32x16_bf16 v[64:79], v[244:247], v[132:135], v[64:79]
	ds_read_b128 v[244:247], v189 offset:50720
	s_waitcnt lgkmcnt(2)
	v_mfma_f32_32x32x16_bf16 v[64:79], v[236:239], v[128:131], v[64:79]
	ds_read_b128 v[236:239], v189 offset:50752
	s_waitcnt lgkmcnt(2)
	v_mfma_f32_32x32x16_bf16 v[112:127], v[240:243], v[112:115], 0
	ds_read_b128 v[240:243], v189 offset:50784
	s_waitcnt lgkmcnt(2)
	v_mfma_f32_32x32x16_bf16 v[112:127], v[244:247], v[184:187], v[112:127]
	ds_read_b128 v[244:247], v189 offset:50816
	s_waitcnt lgkmcnt(2)
	v_mfma_f32_32x32x16_bf16 v[112:127], v[236:239], v[180:183], v[112:127]
	ds_read_b128 v[236:239], v189 offset:50848
	s_waitcnt lgkmcnt(2)
	v_mfma_f32_32x32x16_bf16 v[112:127], v[240:243], v[176:179], v[112:127]
	ds_read_b128 v[240:243], v189 offset:50880
	s_waitcnt lgkmcnt(2)
	v_mfma_f32_32x32x16_bf16 v[112:127], v[244:247], v[172:175], v[112:127]
	ds_read_b128 v[244:247], v189 offset:50912
	s_waitcnt lgkmcnt(2)
	v_mfma_f32_32x32x16_bf16 v[112:127], v[236:239], v[168:171], v[112:127]
	ds_read_b128 v[236:239], v189 offset:50944
	s_waitcnt lgkmcnt(2)
	v_mfma_f32_32x32x16_bf16 v[112:127], v[240:243], v[164:167], v[112:127]
	ds_read_b128 v[240:243], v189 offset:50976
	s_waitcnt lgkmcnt(2)
	v_mfma_f32_32x32x16_bf16 v[112:127], v[244:247], v[160:163], v[112:127]
	ds_read_b128 v[244:247], v189 offset:51008
	s_waitcnt lgkmcnt(2)
	v_mfma_f32_32x32x16_bf16 v[112:127], v[236:239], v[156:159], v[112:127]
	v_lshl_add_u64 v[160:161], s[16:17], 0, v[190:191]
	ds_read_b128 v[236:239], v189 offset:51040
	s_waitcnt lgkmcnt(2)
	v_mfma_f32_32x32x16_bf16 v[112:127], v[240:243], v[152:155], v[112:127]
	v_lshl_add_u64 v[156:157], v[160:161], 0, s[14:15]
	s_mov_b64 s[14:15], 0x5840000
	ds_read_b128 v[240:243], v189 offset:51072
	s_waitcnt lgkmcnt(2)
	v_mfma_f32_32x32x16_bf16 v[112:127], v[244:247], v[148:151], v[112:127]
	v_lshl_add_u64 v[152:153], v[156:157], 0, v[204:205]
	ds_read_b128 v[244:247], v189 offset:51104
	s_waitcnt lgkmcnt(2)
	v_mfma_f32_32x32x16_bf16 v[112:127], v[236:239], v[144:147], v[112:127]
	v_lshl_add_u64 v[148:149], v[156:157], 0, v[202:203]
	ds_read_b128 v[236:239], v189 offset:51136
	s_waitcnt lgkmcnt(2)
	v_mfma_f32_32x32x16_bf16 v[112:127], v[240:243], v[140:143], v[112:127]
	v_lshl_add_u64 v[144:145], v[156:157], 0, v[200:201]
	ds_read_b128 v[240:243], v189 offset:51168
	s_waitcnt lgkmcnt(2)
	v_mfma_f32_32x32x16_bf16 v[112:127], v[244:247], v[136:139], v[112:127]
	v_lshl_add_u64 v[140:141], v[156:157], 0, v[198:199]
	s_waitcnt lgkmcnt(1)
	v_mfma_f32_32x32x16_bf16 v[112:127], v[236:239], v[132:135], v[112:127]
	s_waitcnt lgkmcnt(0)
	s_barrier
; #define LAS __attribute__((address_space(3)))
; __device__ __forceinline__ void stage_half(const bf16* g, LAS bf16* dst, int tid) {
;     v4u t[8];
; #pragma unroll
;     for (int i = 0; i < 8; ++i) { const int ch = tid + i * NT, r = ch >> 5, cc = ch & 31; t[i] = *(const v4u*)(g + (size_t)r * 1024 + cc * 8); }
; #pragma unroll
;     for (int i = 0; i < 8; ++i) { const int ch = tid + i * NT, r = ch >> 5, cc = ch & 31; *(LAS v4u*)(dst + r * XP + cc * 8) = t[i]; }
; }
; __device__ __forceinline__ void xattn_core(unsigned char* ws, LAS unsigned char* lds, int b, int hd, int qb, int tid, const bf16x8 (&qf)[16]) {
;     ...
;     __syncthreads();
;     stage_half(Vg, L0, tid); stage_half(Vg + (size_t)128 * 1024, L1, tid);
;     float mx = -3.0e38f;
; #pragma unroll
;     for (int mt = 0; mt < 8; ++mt)
; #pragma unroll
;         for (int r = 0; r < 16; ++r) mx = fmaxf(mx, sacc[mt][r]);
;     mx = fmaxf(mx, __shfl_xor(mx, 32));
	v_lshl_add_u64 v[136:137], v[156:157], 0, v[196:197]
	global_load_dwordx4 v[136:139], v[136:137], off
	v_mov_b32_e32 v189, v191
	s_waitcnt lgkmcnt(0)
	v_mfma_f32_32x32x16_bf16 v[112:127], v[240:243], v[128:131], v[112:127]
	v_lshl_add_u64 v[128:129], v[156:157], 0, v[192:193]
	global_load_dwordx4 v[128:131], v[128:129], off
	v_lshl_add_u64 v[132:133], v[156:157], 0, v[194:195]
	global_load_dwordx4 v[132:135], v[132:133], off
	v_lshl_add_u64 v[156:157], v[156:157], 0, v[206:207]
	global_load_dwordx4 v[140:143], v[140:141], off
	s_nop 0
	global_load_dwordx4 v[144:147], v[144:145], off
	s_nop 0
	global_load_dwordx4 v[148:151], v[148:149], off
	s_nop 0
	global_load_dwordx4 v[152:155], v[152:153], off
	s_nop 0
	global_load_dwordx4 v[156:159], v[156:157], off
	s_waitcnt vmcnt(6)
	ds_write_b128 v223, v[128:131]
	s_waitcnt vmcnt(5)
	ds_write_b128 v222, v[132:135]
	ds_write_b128 v221, v[136:139]
	s_waitcnt vmcnt(4)
	ds_write_b128 v220, v[140:143]
	s_waitcnt vmcnt(3)
	ds_write_b128 v219, v[144:147]
	s_waitcnt vmcnt(2)
	ds_write_b128 v218, v[148:151]
	s_waitcnt vmcnt(1)
	ds_write_b128 v217, v[152:155]
	s_waitcnt vmcnt(0)
	ds_write_b128 v216, v[156:159]
	v_lshl_add_u64 v[156:157], v[160:161], 0, s[14:15]
	v_lshl_add_u64 v[128:129], v[156:157], 0, v[192:193]
	global_load_dwordx4 v[128:131], v[128:129], off
	v_lshl_add_u64 v[132:133], v[156:157], 0, v[194:195]
	global_load_dwordx4 v[132:135], v[132:133], off
	v_lshl_add_u64 v[136:137], v[156:157], 0, v[196:197]
	global_load_dwordx4 v[136:139], v[136:137], off
	v_lshl_add_u64 v[140:141], v[156:157], 0, v[198:199]
	global_load_dwordx4 v[140:143], v[140:141], off
	v_lshl_add_u64 v[144:145], v[156:157], 0, v[200:201]
	global_load_dwordx4 v[144:147], v[144:145], off
	v_lshl_add_u64 v[148:149], v[156:157], 0, v[202:203]
	global_load_dwordx4 v[148:151], v[148:149], off
	v_lshl_add_u64 v[152:153], v[156:157], 0, v[204:205]
	global_load_dwordx4 v[152:155], v[152:153], off
	v_lshl_add_u64 v[156:157], v[156:157], 0, v[206:207]
	global_load_dwordx4 v[156:159], v[156:157], off
	s_waitcnt vmcnt(7)
	ds_write_b128 v230, v[128:131]
	s_waitcnt vmcnt(6)
	ds_write_b128 v224, v[132:135]
	s_waitcnt vmcnt(5)
	ds_write_b128 v225, v[136:139]
	s_waitcnt vmcnt(4)
	ds_write_b128 v226, v[140:143]
	s_waitcnt vmcnt(3)
	ds_write_b128 v227, v[144:147]
	s_waitcnt vmcnt(2)
	ds_write_b128 v228, v[148:151]
	s_waitcnt vmcnt(1)
	ds_write_b128 v229, v[152:155]
	s_waitcnt vmcnt(0)
	ds_write_b128 v215, v[156:159]
	v_max3_f32 v128, v96, s7, v97
	v_max3_f32 v128, v128, v98, v99
	v_max3_f32 v128, v128, v100, v101
	v_max3_f32 v128, v128, v102, v103
	v_max3_f32 v128, v128, v104, v105
	v_max3_f32 v128, v128, v106, v107
	v_max3_f32 v128, v128, v108, v109
	v_max3_f32 v128, v128, v110, v111
	v_max3_f32 v128, v128, v32, v33
	v_max3_f32 v128, v128, v34, v35
	v_max3_f32 v128, v128, v36, v37
	v_max3_f32 v128, v128, v38, v39
	v_max3_f32 v128, v128, v40, v41
	v_max3_f32 v128, v128, v42, v43
	v_max3_f32 v128, v128, v44, v45
	v_max3_f32 v128, v128, v46, v47
	v_max3_f32 v128, v128, v16, v17
	v_max3_f32 v128, v128, v18, v19
	v_max3_f32 v128, v128, v20, v21
	v_max3_f32 v128, v128, v22, v23
	v_max3_f32 v128, v128, v24, v25
	v_max3_f32 v128, v128, v26, v27
	v_max3_f32 v128, v128, v28, v29
	v_max3_f32 v128, v128, v30, v31
	v_max3_f32 v128, v128, v0, v1
	v_max3_f32 v128, v128, v2, v3
	v_max3_f32 v128, v128, v4, v5
	v_max3_f32 v128, v128, v6, v7
	v_max3_f32 v128, v128, v8, v9
	v_max3_f32 v128, v128, v10, v11
	v_max3_f32 v128, v128, v12, v13
	v_max3_f32 v128, v128, v14, v15
	v_max3_f32 v128, v128, v48, v49
	v_max3_f32 v128, v128, v50, v51
	v_max3_f32 v128, v128, v52, v53
	v_max3_f32 v128, v128, v54, v55
	v_max3_f32 v128, v128, v56, v57
	v_max3_f32 v128, v128, v58, v59
	v_max3_f32 v128, v128, v60, v61
	v_max3_f32 v128, v128, v62, v63
	v_max3_f32 v128, v128, v80, v81
	v_max3_f32 v128, v128, v82, v83
	v_max3_f32 v128, v128, v84, v85
	v_max3_f32 v128, v128, v86, v87
	v_max3_f32 v128, v128, v88, v89
	v_max3_f32 v128, v128, v90, v91
	v_max3_f32 v128, v128, v92, v93
	v_max3_f32 v128, v128, v94, v95
	v_max3_f32 v128, v128, v64, v65
	v_max3_f32 v128, v128, v66, v67
	v_max3_f32 v128, v128, v68, v69
	v_max3_f32 v128, v128, v70, v71
	v_max3_f32 v128, v128, v72, v73
	v_max3_f32 v128, v128, v74, v75
	v_max3_f32 v128, v128, v76, v77
	v_max3_f32 v128, v128, v78, v79
	v_max3_f32 v128, v128, v112, v113
	v_max3_f32 v128, v128, v114, v115
	v_max3_f32 v128, v128, v116, v117
	v_max3_f32 v128, v128, v118, v119
	v_max3_f32 v128, v128, v120, v121
	v_max3_f32 v128, v128, v122, v123
	v_max3_f32 v128, v128, v124, v125
	v_max3_f32 v129, v128, v126, v127
	v_mbcnt_lo_u32_b32 v128, -1, 0
	v_mbcnt_hi_u32_b32 v128, -1, v128
	v_and_b32_e32 v131, 64, v128
	v_xor_b32_e32 v130, 32, v128
	v_add_u32_e32 v131, 64, v131
	v_cmp_lt_i32_e32 vcc, v130, v131
	s_waitcnt lgkmcnt(0)
	s_barrier
; __device__ __forceinline__ unsigned pk2(float lo, float hi) { return pg8::cvt_pk_bf16(lo, hi); }
; __device__ __forceinline__ void xattn_core(unsigned char* ws, LAS unsigned char* lds, int b, int hd, int qb, int tid, const bf16x8 (&qf)[16]) {
;     ...
;     float mx = -3.0e38f;
; #pragma unroll
;     for (int mt = 0; mt < 8; ++mt)
; #pragma unroll
;         for (int r = 0; r < 16; ++r) mx = fmaxf(mx, sacc[mt][r]);
;     mx = fmaxf(mx, __shfl_xor(mx, 32));
;     float sum = 0.f; bf16x8 pf[8][2];
; #pragma unroll
;     for (int mt = 0; mt < 8; ++mt) {
;         float e[16];
; #pragma unroll
;         for (int r = 0; r < 16; ++r) { e[r] = __expf(sacc[mt][r] - mx); sum += e[r]; }
; #pragma unroll
;         for (int s = 0; s < 2; ++s) { v4u w; w.x = pk2(e[8 * s], e[8 * s + 1]); w.y = pk2(e[8 * s + 2], e[8 * s + 3]); w.z = pk2(e[8 * s + 4], e[8 * s + 5]); w.w = pk2(e[8 * s + 6], e[8 * s + 7]); pf[mt][s] = __builtin_bit_cast(bf16x8, w); }
;     }
	v_cndmask_b32_e32 v128, v128, v130, vcc
	v_lshlrev_b32_e32 v128, 2, v128
	ds_bpermute_b32 v130, v128, v129
	s_waitcnt lgkmcnt(0)
	v_max_f32_e32 v130, v130, v130
	v_max_f32_e32 v129, v129, v130
	v_sub_f32_e32 v96, v96, v129
	v_mul_f32_e32 v96, 0x3fb8aa3b, v96
	v_exp_f32_e32 v130, v96
	v_sub_f32_e32 v96, v97, v129
	v_mul_f32_e32 v96, 0x3fb8aa3b, v96
	v_exp_f32_e32 v131, v96
	v_sub_f32_e32 v96, v98, v129
	v_mul_f32_e32 v96, 0x3fb8aa3b, v96
	v_exp_f32_e32 v132, v96
	v_sub_f32_e32 v96, v99, v129
	v_mul_f32_e32 v96, 0x3fb8aa3b, v96
	v_exp_f32_e32 v133, v96
	v_sub_f32_e32 v96, v100, v129
	v_mul_f32_e32 v96, 0x3fb8aa3b, v96
	v_exp_f32_e32 v134, v96
	v_sub_f32_e32 v96, v101, v129
	v_mul_f32_e32 v96, 0x3fb8aa3b, v96
	v_exp_f32_e32 v135, v96
	v_sub_f32_e32 v96, v102, v129
	v_mul_f32_e32 v96, 0x3fb8aa3b, v96
	v_exp_f32_e32 v136, v96
	v_sub_f32_e32 v96, v103, v129
	v_mul_f32_e32 v96, 0x3fb8aa3b, v96
	v_exp_f32_e32 v137, v96
	v_sub_f32_e32 v96, v104, v129
	v_mul_f32_e32 v96, 0x3fb8aa3b, v96
	v_exp_f32_e32 v104, v96
	v_sub_f32_e32 v96, v105, v129
	v_mul_f32_e32 v96, 0x3fb8aa3b, v96
	v_exp_f32_e32 v105, v96
	v_sub_f32_e32 v96, v106, v129
	v_mul_f32_e32 v96, 0x3fb8aa3b, v96
	v_exp_f32_e32 v106, v96
	v_sub_f32_e32 v96, v107, v129
	v_mul_f32_e32 v96, 0x3fb8aa3b, v96
	v_exp_f32_e32 v107, v96
	v_sub_f32_e32 v96, v108, v129
	v_mul_f32_e32 v96, 0x3fb8aa3b, v96
	v_exp_f32_e32 v108, v96
	v_sub_f32_e32 v96, v109, v129
	v_mul_f32_e32 v96, 0x3fb8aa3b, v96
	v_exp_f32_e32 v109, v96
	v_sub_f32_e32 v96, v110, v129
	v_mul_f32_e32 v96, 0x3fb8aa3b, v96
	v_exp_f32_e32 v110, v96
	v_sub_f32_e32 v96, v111, v129
	v_mul_f32_e32 v96, 0x3fb8aa3b, v96
	v_exp_f32_e32 v111, v96
	v_cvt_pk_bf16_f32 v96, v130, v131
	v_add_f32_e32 v130, 0, v130
	v_add_f32_e32 v130, v131, v130
	v_add_f32_e32 v130, v132, v130
	v_add_f32_e32 v130, v133, v130
	v_add_f32_e32 v130, v134, v130
	v_add_f32_e32 v130, v135, v130
	v_add_f32_e32 v130, v136, v130
	v_add_f32_e32 v130, v137, v130
	v_sub_f32_e32 v32, v32, v129
	v_cvt_pk_bf16_f32 v100, v104, v105
	v_add_f32_e32 v104, v104, v130
	v_mul_f32_e32 v32, 0x3fb8aa3b, v32
	v_add_f32_e32 v104, v105, v104
	v_exp_f32_e32 v105, v32
	v_sub_f32_e32 v32, v33, v129
	v_mul_f32_e32 v32, 0x3fb8aa3b, v32
	v_cvt_pk_bf16_f32 v101, v106, v107
	v_add_f32_e32 v104, v106, v104
	v_exp_f32_e32 v106, v32
	v_sub_f32_e32 v32, v34, v129
	v_mul_f32_e32 v32, 0x3fb8aa3b, v32
	v_add_f32_e32 v104, v107, v104
	v_exp_f32_e32 v107, v32
	v_sub_f32_e32 v32, v35, v129
	v_mul_f32_e32 v32, 0x3fb8aa3b, v32
	v_cvt_pk_bf16_f32 v102, v108, v109
	v_add_f32_e32 v104, v108, v104
	v_exp_f32_e32 v108, v32
	v_sub_f32_e32 v32, v36, v129
	v_mul_f32_e32 v32, 0x3fb8aa3b, v32
	v_add_f32_e32 v104, v109, v104
	v_exp_f32_e32 v109, v32
	v_sub_f32_e32 v32, v37, v129
	v_mul_f32_e32 v32, 0x3fb8aa3b, v32
	v_cvt_pk_bf16_f32 v103, v110, v111
	v_add_f32_e32 v104, v110, v104
	v_exp_f32_e32 v110, v32
	v_sub_f32_e32 v32, v38, v129
	v_mul_f32_e32 v32, 0x3fb8aa3b, v32
	v_add_f32_e32 v104, v111, v104
	v_exp_f32_e32 v111, v32
	v_sub_f32_e32 v32, v39, v129
	v_mul_f32_e32 v32, 0x3fb8aa3b, v32
	v_exp_f32_e32 v130, v32
	v_sub_f32_e32 v32, v40, v129
	v_mul_f32_e32 v32, 0x3fb8aa3b, v32
	v_add_f32_e32 v104, v105, v104
	v_exp_f32_e32 v40, v32
	v_sub_f32_e32 v32, v41, v129
	v_add_f32_e32 v104, v106, v104
	v_mul_f32_e32 v32, 0x3fb8aa3b, v32
	v_add_f32_e32 v104, v107, v104
	v_exp_f32_e32 v41, v32
	v_sub_f32_e32 v32, v42, v129
	v_add_f32_e32 v104, v108, v104
	v_mul_f32_e32 v32, 0x3fb8aa3b, v32
	v_add_f32_e32 v104, v109, v104
	v_exp_f32_e32 v42, v32
	v_sub_f32_e32 v32, v43, v129
	v_add_f32_e32 v104, v110, v104
	v_mul_f32_e32 v32, 0x3fb8aa3b, v32
	v_add_f32_e32 v104, v111, v104
	v_exp_f32_e32 v43, v32
	v_sub_f32_e32 v32, v44, v129
	v_add_f32_e32 v104, v130, v104
	v_sub_f32_e32 v16, v16, v129
	v_mul_f32_e32 v32, 0x3fb8aa3b, v32
	v_cvt_pk_bf16_f32 v36, v40, v41
	v_add_f32_e32 v40, v40, v104
	v_mul_f32_e32 v16, 0x3fb8aa3b, v16
	v_exp_f32_e32 v44, v32
	v_sub_f32_e32 v32, v45, v129
	v_add_f32_e32 v40, v41, v40
	v_exp_f32_e32 v41, v16
	v_sub_f32_e32 v16, v17, v129
	v_mul_f32_e32 v32, 0x3fb8aa3b, v32
	v_mul_f32_e32 v16, 0x3fb8aa3b, v16
	v_exp_f32_e32 v45, v32
	v_sub_f32_e32 v32, v46, v129
	v_cvt_pk_bf16_f32 v37, v42, v43
	v_add_f32_e32 v40, v42, v40
	v_exp_f32_e32 v42, v16
	v_sub_f32_e32 v16, v18, v129
	v_mul_f32_e32 v32, 0x3fb8aa3b, v32
	v_mul_f32_e32 v16, 0x3fb8aa3b, v16
	v_exp_f32_e32 v46, v32
	v_sub_f32_e32 v32, v47, v129
	v_add_f32_e32 v40, v43, v40
	v_exp_f32_e32 v43, v16
	v_sub_f32_e32 v16, v19, v129
	v_mul_f32_e32 v32, 0x3fb8aa3b, v32
	v_mul_f32_e32 v16, 0x3fb8aa3b, v16
	v_exp_f32_e32 v47, v32
	v_cvt_pk_bf16_f32 v38, v44, v45
	v_add_f32_e32 v40, v44, v40
	v_exp_f32_e32 v44, v16
	v_sub_f32_e32 v16, v20, v129
	v_mul_f32_e32 v16, 0x3fb8aa3b, v16
	v_add_f32_e32 v40, v45, v40
	v_exp_f32_e32 v45, v16
	v_sub_f32_e32 v16, v21, v129
	v_mul_f32_e32 v16, 0x3fb8aa3b, v16
	v_cvt_pk_bf16_f32 v39, v46, v47
	v_add_f32_e32 v40, v46, v40
	v_exp_f32_e32 v46, v16
	v_sub_f32_e32 v16, v22, v129
	v_mul_f32_e32 v16, 0x3fb8aa3b, v16
	v_add_f32_e32 v40, v47, v40
	v_exp_f32_e32 v47, v16
	v_sub_f32_e32 v16, v23, v129
	v_mul_f32_e32 v16, 0x3fb8aa3b, v16
	v_exp_f32_e32 v104, v16
	v_sub_f32_e32 v16, v24, v129
	v_mul_f32_e32 v16, 0x3fb8aa3b, v16
	v_exp_f32_e32 v24, v16
	v_sub_f32_e32 v16, v25, v129
	v_mul_f32_e32 v16, 0x3fb8aa3b, v16
	v_exp_f32_e32 v25, v16
	v_sub_f32_e32 v16, v26, v129
	v_mul_f32_e32 v16, 0x3fb8aa3b, v16
	v_add_f32_e32 v40, v41, v40
	v_exp_f32_e32 v26, v16
	v_sub_f32_e32 v16, v27, v129
	v_add_f32_e32 v40, v42, v40
	v_mul_f32_e32 v16, 0x3fb8aa3b, v16
	v_add_f32_e32 v40, v43, v40
	v_exp_f32_e32 v27, v16
	v_sub_f32_e32 v16, v28, v129
	v_add_f32_e32 v40, v44, v40
; __device__ __forceinline__ unsigned pk2(float lo, float hi) { return pg8::cvt_pk_bf16(lo, hi); }
; __device__ __forceinline__ void xattn_core(unsigned char* ws, LAS unsigned char* lds, int b, int hd, int qb, int tid, const bf16x8 (&qf)[16]) {
;     ...
;     float mx = -3.0e38f;
; #pragma unroll
;     for (int mt = 0; mt < 8; ++mt)
; #pragma unroll
;         for (int r = 0; r < 16; ++r) mx = fmaxf(mx, sacc[mt][r]);
;     mx = fmaxf(mx, __shfl_xor(mx, 32));
;     float sum = 0.f; bf16x8 pf[8][2];
; #pragma unroll
;     for (int mt = 0; mt < 8; ++mt) {
;         float e[16];
; #pragma unroll
;         for (int r = 0; r < 16; ++r) { e[r] = __expf(sacc[mt][r] - mx); sum += e[r]; }
; #pragma unroll
;         for (int s = 0; s < 2; ++s) { v4u w; w.x = pk2(e[8 * s], e[8 * s + 1]); w.y = pk2(e[8 * s + 2], e[8 * s + 3]); w.z = pk2(e[8 * s + 4], e[8 * s + 5]); w.w = pk2(e[8 * s + 6], e[8 * s + 7]); pf[mt][s] = __builtin_bit_cast(bf16x8, w); }
;     }
	v_mul_f32_e32 v16, 0x3fb8aa3b, v16
	v_add_f32_e32 v40, v45, v40
	v_exp_f32_e32 v28, v16
	v_sub_f32_e32 v16, v29, v129
	v_add_f32_e32 v40, v46, v40
	v_mul_f32_e32 v16, 0x3fb8aa3b, v16
	v_add_f32_e32 v40, v47, v40
	v_exp_f32_e32 v29, v16
	v_sub_f32_e32 v16, v30, v129
	v_add_f32_e32 v40, v104, v40
	v_mul_f32_e32 v16, 0x3fb8aa3b, v16
	v_cvt_pk_bf16_f32 v20, v24, v25
	v_add_f32_e32 v24, v24, v40
	v_exp_f32_e32 v30, v16
	v_sub_f32_e32 v16, v31, v129
	v_add_f32_e32 v24, v25, v24
	v_mul_f32_e32 v16, 0x3fb8aa3b, v16
	v_add_f32_e32 v24, v26, v24
	v_sub_f32_e32 v0, v0, v129
	v_sub_f32_e32 v1, v1, v129
	v_exp_f32_e32 v31, v16
	v_add_f32_e32 v24, v27, v24
	v_mul_f32_e32 v0, 0x3fb8aa3b, v0
	v_mul_f32_e32 v1, 0x3fb8aa3b, v1
	v_add_f32_e32 v24, v28, v24
	v_exp_f32_e32 v0, v0
	v_exp_f32_e32 v1, v1
	v_sub_f32_e32 v2, v2, v129
	v_add_f32_e32 v24, v29, v24
	v_mul_f32_e32 v2, 0x3fb8aa3b, v2
	v_sub_f32_e32 v3, v3, v129
	v_add_f32_e32 v24, v30, v24
	v_exp_f32_e32 v2, v2
	v_mul_f32_e32 v3, 0x3fb8aa3b, v3
	v_sub_f32_e32 v4, v4, v129
	v_add_f32_e32 v40, v31, v24
	v_exp_f32_e32 v3, v3
	v_mul_f32_e32 v4, 0x3fb8aa3b, v4
	v_sub_f32_e32 v5, v5, v129
	v_exp_f32_e32 v4, v4
	v_mul_f32_e32 v5, 0x3fb8aa3b, v5
	v_sub_f32_e32 v6, v6, v129
	v_cvt_pk_bf16_f32 v24, v0, v1
	v_add_f32_e32 v0, v0, v40
	v_exp_f32_e32 v5, v5
	v_mul_f32_e32 v6, 0x3fb8aa3b, v6
	v_sub_f32_e32 v7, v7, v129
	v_add_f32_e32 v0, v1, v0
	v_exp_f32_e32 v6, v6
	v_mul_f32_e32 v7, 0x3fb8aa3b, v7
	v_sub_f32_e32 v8, v8, v129
	v_add_f32_e32 v0, v2, v0
	v_exp_f32_e32 v7, v7
	v_mul_f32_e32 v8, 0x3fb8aa3b, v8
	v_sub_f32_e32 v9, v9, v129
	v_add_f32_e32 v0, v3, v0
	v_exp_f32_e32 v8, v8
	v_mul_f32_e32 v9, 0x3fb8aa3b, v9
	v_sub_f32_e32 v10, v10, v129
	v_add_f32_e32 v0, v4, v0
	v_exp_f32_e32 v9, v9
	v_mul_f32_e32 v10, 0x3fb8aa3b, v10
	v_sub_f32_e32 v11, v11, v129
	v_add_f32_e32 v0, v5, v0
	v_exp_f32_e32 v10, v10
	v_mul_f32_e32 v11, 0x3fb8aa3b, v11
	v_sub_f32_e32 v12, v12, v129
	v_add_f32_e32 v0, v6, v0
	v_exp_f32_e32 v11, v11
	v_mul_f32_e32 v12, 0x3fb8aa3b, v12
	v_sub_f32_e32 v13, v13, v129
	v_add_f32_e32 v0, v7, v0
	v_exp_f32_e32 v12, v12
	v_mul_f32_e32 v13, 0x3fb8aa3b, v13
	v_sub_f32_e32 v14, v14, v129
	v_add_f32_e32 v0, v8, v0
	v_exp_f32_e32 v13, v13
	v_mul_f32_e32 v14, 0x3fb8aa3b, v14
	v_sub_f32_e32 v15, v15, v129
	v_add_f32_e32 v0, v9, v0
	v_exp_f32_e32 v14, v14
	v_mul_f32_e32 v15, 0x3fb8aa3b, v15
	v_add_f32_e32 v0, v10, v0
	v_sub_f32_e32 v1, v48, v129
	v_exp_f32_e32 v15, v15
	v_cvt_pk_bf16_f32 v25, v2, v3
	v_add_f32_e32 v0, v11, v0
	v_mul_f32_e32 v1, 0x3fb8aa3b, v1
	v_sub_f32_e32 v2, v49, v129
	v_add_f32_e32 v0, v12, v0
	v_exp_f32_e32 v1, v1
	v_mul_f32_e32 v2, 0x3fb8aa3b, v2
	v_sub_f32_e32 v3, v50, v129
	v_cvt_pk_bf16_f32 v21, v26, v27
	v_cvt_pk_bf16_f32 v26, v4, v5
	v_add_f32_e32 v0, v13, v0
	v_exp_f32_e32 v2, v2
	v_mul_f32_e32 v3, 0x3fb8aa3b, v3
	v_sub_f32_e32 v4, v51, v129
	v_add_f32_e32 v0, v14, v0
	v_exp_f32_e32 v3, v3
	v_mul_f32_e32 v4, 0x3fb8aa3b, v4
	v_sub_f32_e32 v5, v52, v129
	v_cvt_pk_bf16_f32 v27, v6, v7
	v_add_f32_e32 v0, v15, v0
	v_exp_f32_e32 v4, v4
	v_mul_f32_e32 v5, 0x3fb8aa3b, v5
	v_sub_f32_e32 v6, v53, v129
	v_exp_f32_e32 v5, v5
	v_mul_f32_e32 v6, 0x3fb8aa3b, v6
	v_sub_f32_e32 v7, v54, v129
	v_add_f32_e32 v0, v1, v0
	v_cvt_pk_bf16_f32 v22, v28, v29
	v_cvt_pk_bf16_f32 v28, v8, v9
	v_exp_f32_e32 v6, v6
	v_mul_f32_e32 v7, 0x3fb8aa3b, v7
	v_sub_f32_e32 v8, v55, v129
	v_add_f32_e32 v0, v2, v0
	v_exp_f32_e32 v7, v7
	v_mul_f32_e32 v8, 0x3fb8aa3b, v8
	v_sub_f32_e32 v9, v56, v129
	v_add_f32_e32 v0, v3, v0
	v_cvt_pk_bf16_f32 v29, v10, v11
	v_exp_f32_e32 v8, v8
	v_mul_f32_e32 v9, 0x3fb8aa3b, v9
	v_sub_f32_e32 v10, v57, v129
	v_add_f32_e32 v0, v4, v0
	v_exp_f32_e32 v9, v9
	v_mul_f32_e32 v10, 0x3fb8aa3b, v10
	v_sub_f32_e32 v11, v58, v129
	v_add_f32_e32 v0, v5, v0
	v_cvt_pk_bf16_f32 v23, v30, v31
	v_cvt_pk_bf16_f32 v30, v12, v13
	v_exp_f32_e32 v10, v10
	v_mul_f32_e32 v11, 0x3fb8aa3b, v11
	v_sub_f32_e32 v12, v59, v129
	v_add_f32_e32 v0, v6, v0
	v_exp_f32_e32 v11, v11
	v_mul_f32_e32 v12, 0x3fb8aa3b, v12
	v_sub_f32_e32 v13, v60, v129
	v_add_f32_e32 v0, v7, v0
	v_cvt_pk_bf16_f32 v31, v14, v15
	v_exp_f32_e32 v12, v12
	v_mul_f32_e32 v13, 0x3fb8aa3b, v13
	v_sub_f32_e32 v14, v61, v129
	v_add_f32_e32 v0, v8, v0
	v_exp_f32_e32 v13, v13
	v_mul_f32_e32 v14, 0x3fb8aa3b, v14
	v_sub_f32_e32 v15, v62, v129
	v_sub_f32_e32 v40, v63, v129
	v_add_f32_e32 v0, v9, v0
	v_exp_f32_e32 v14, v14
	v_mul_f32_e32 v15, 0x3fb8aa3b, v15
	v_mul_f32_e32 v40, 0x3fb8aa3b, v40
	v_add_f32_e32 v0, v10, v0
	v_exp_f32_e32 v15, v15
	v_exp_f32_e32 v48, v40
	v_cvt_pk_bf16_f32 v40, v1, v2
	v_add_f32_e32 v0, v11, v0
	v_sub_f32_e32 v1, v80, v129
	v_add_f32_e32 v0, v12, v0
	v_mul_f32_e32 v1, 0x3fb8aa3b, v1
	v_sub_f32_e32 v2, v81, v129
	v_cvt_pk_bf16_f32 v16, v41, v42
	v_cvt_pk_bf16_f32 v41, v3, v4
	v_add_f32_e32 v0, v13, v0
	v_exp_f32_e32 v1, v1
	v_mul_f32_e32 v2, 0x3fb8aa3b, v2
	v_sub_f32_e32 v3, v82, v129
	v_add_f32_e32 v0, v14, v0
	v_exp_f32_e32 v2, v2
	v_mul_f32_e32 v3, 0x3fb8aa3b, v3
	v_sub_f32_e32 v4, v83, v129
	v_cvt_pk_bf16_f32 v42, v5, v6
	v_add_f32_e32 v0, v15, v0
	v_exp_f32_e32 v3, v3
	v_mul_f32_e32 v4, 0x3fb8aa3b, v4
	v_sub_f32_e32 v5, v84, v129
	v_add_f32_e32 v0, v48, v0
	v_exp_f32_e32 v4, v4
	v_mul_f32_e32 v5, 0x3fb8aa3b, v5
	v_sub_f32_e32 v6, v85, v129
	v_cvt_pk_bf16_f32 v17, v43, v44
	v_cvt_pk_bf16_f32 v43, v7, v8
	v_exp_f32_e32 v5, v5
	v_mul_f32_e32 v6, 0x3fb8aa3b, v6
	v_sub_f32_e32 v7, v86, v129
	v_add_f32_e32 v0, v1, v0
	v_exp_f32_e32 v6, v6
	v_mul_f32_e32 v7, 0x3fb8aa3b, v7
	v_sub_f32_e32 v8, v87, v129
	v_add_f32_e32 v0, v2, v0
	v_cvt_pk_bf16_f32 v44, v9, v10
	v_exp_f32_e32 v7, v7
	v_mul_f32_e32 v8, 0x3fb8aa3b, v8
	v_sub_f32_e32 v9, v88, v129
; __device__ __forceinline__ unsigned pk2(float lo, float hi) { return pg8::cvt_pk_bf16(lo, hi); }
; __device__ __forceinline__ void xattn_core(unsigned char* ws, LAS unsigned char* lds, int b, int hd, int qb, int tid, const bf16x8 (&qf)[16]) {
;     ...
;     float sum = 0.f; bf16x8 pf[8][2];
; #pragma unroll
;     for (int mt = 0; mt < 8; ++mt) {
;         float e[16];
; #pragma unroll
;         for (int r = 0; r < 16; ++r) { e[r] = __expf(sacc[mt][r] - mx); sum += e[r]; }
; #pragma unroll
;         for (int s = 0; s < 2; ++s) { v4u w; w.x = pk2(e[8 * s], e[8 * s + 1]); w.y = pk2(e[8 * s + 2], e[8 * s + 3]); w.z = pk2(e[8 * s + 4], e[8 * s + 5]); w.w = pk2(e[8 * s + 6], e[8 * s + 7]); pf[mt][s] = __builtin_bit_cast(bf16x8, w); }
;     }
;     sum += __shfl_xor(sum, 32);
;     const float inv = 1.f / sum;
;     __syncthreads();
;     bf16* op = (bf16*)(ws + WS_O) + (size_t)(q0 + r32) * 1024 + hd * 256 + 4 * hh;
	v_add_f32_e32 v0, v3, v0
	v_exp_f32_e32 v8, v8
	v_mul_f32_e32 v9, 0x3fb8aa3b, v9
	v_sub_f32_e32 v10, v89, v129
	v_add_f32_e32 v0, v4, v0
	v_cvt_pk_bf16_f32 v18, v45, v46
	v_cvt_pk_bf16_f32 v45, v11, v12
	v_exp_f32_e32 v9, v9
	v_mul_f32_e32 v10, 0x3fb8aa3b, v10
	v_sub_f32_e32 v11, v90, v129
	v_add_f32_e32 v0, v5, v0
	v_exp_f32_e32 v10, v10
	v_mul_f32_e32 v11, 0x3fb8aa3b, v11
	v_sub_f32_e32 v12, v91, v129
	v_add_f32_e32 v0, v6, v0
	v_cvt_pk_bf16_f32 v46, v13, v14
	v_exp_f32_e32 v11, v11
	v_mul_f32_e32 v12, 0x3fb8aa3b, v12
	v_sub_f32_e32 v13, v92, v129
	v_add_f32_e32 v0, v7, v0
	v_exp_f32_e32 v12, v12
	v_mul_f32_e32 v13, 0x3fb8aa3b, v13
	v_sub_f32_e32 v14, v93, v129
	v_add_f32_e32 v0, v8, v0
	v_cvt_pk_bf16_f32 v19, v47, v104
	v_cvt_pk_bf16_f32 v47, v15, v48
	v_exp_f32_e32 v13, v13
	v_mul_f32_e32 v14, 0x3fb8aa3b, v14
	v_sub_f32_e32 v15, v94, v129
	v_sub_f32_e32 v48, v95, v129
	v_add_f32_e32 v0, v9, v0
	v_exp_f32_e32 v14, v14
	v_mul_f32_e32 v15, 0x3fb8aa3b, v15
	v_mul_f32_e32 v48, 0x3fb8aa3b, v48
	v_add_f32_e32 v0, v10, v0
	v_exp_f32_e32 v15, v15
	v_exp_f32_e32 v56, v48
	v_cvt_pk_bf16_f32 v48, v1, v2
	v_add_f32_e32 v0, v11, v0
	v_sub_f32_e32 v1, v64, v129
	v_add_f32_e32 v0, v12, v0
	v_mul_f32_e32 v1, 0x3fb8aa3b, v1
	v_sub_f32_e32 v2, v65, v129
	v_cvt_pk_bf16_f32 v49, v3, v4
	v_add_f32_e32 v0, v13, v0
	v_exp_f32_e32 v1, v1
	v_mul_f32_e32 v2, 0x3fb8aa3b, v2
	v_sub_f32_e32 v3, v66, v129
	v_add_f32_e32 v0, v14, v0
	v_exp_f32_e32 v2, v2
	v_mul_f32_e32 v3, 0x3fb8aa3b, v3
	v_sub_f32_e32 v4, v67, v129
	v_cvt_pk_bf16_f32 v50, v5, v6
	v_add_f32_e32 v0, v15, v0
	v_exp_f32_e32 v3, v3
	v_mul_f32_e32 v4, 0x3fb8aa3b, v4
	v_sub_f32_e32 v5, v68, v129
	v_add_f32_e32 v0, v56, v0
	v_exp_f32_e32 v4, v4
	v_mul_f32_e32 v5, 0x3fb8aa3b, v5
	v_sub_f32_e32 v6, v69, v129
	v_cvt_pk_bf16_f32 v51, v7, v8
	v_exp_f32_e32 v5, v5
	v_mul_f32_e32 v6, 0x3fb8aa3b, v6
	v_sub_f32_e32 v7, v70, v129
	v_add_f32_e32 v0, v1, v0
	v_exp_f32_e32 v6, v6
	v_mul_f32_e32 v7, 0x3fb8aa3b, v7
	v_sub_f32_e32 v8, v71, v129
	v_add_f32_e32 v0, v2, v0
	v_cvt_pk_bf16_f32 v52, v9, v10
	v_exp_f32_e32 v7, v7
	v_mul_f32_e32 v8, 0x3fb8aa3b, v8
	v_sub_f32_e32 v9, v72, v129
	v_add_f32_e32 v0, v3, v0
	v_exp_f32_e32 v8, v8
	v_mul_f32_e32 v9, 0x3fb8aa3b, v9
	v_sub_f32_e32 v10, v73, v129
	v_add_f32_e32 v0, v4, v0
	v_cvt_pk_bf16_f32 v53, v11, v12
	v_exp_f32_e32 v9, v9
	v_mul_f32_e32 v10, 0x3fb8aa3b, v10
	v_sub_f32_e32 v11, v74, v129
	v_add_f32_e32 v0, v5, v0
	v_exp_f32_e32 v10, v10
	v_mul_f32_e32 v11, 0x3fb8aa3b, v11
	v_sub_f32_e32 v12, v75, v129
	v_add_f32_e32 v0, v6, v0
	v_cvt_pk_bf16_f32 v54, v13, v14
	v_exp_f32_e32 v11, v11
	v_mul_f32_e32 v12, 0x3fb8aa3b, v12
	v_sub_f32_e32 v13, v76, v129
	v_add_f32_e32 v0, v7, v0
	v_exp_f32_e32 v12, v12
	v_mul_f32_e32 v13, 0x3fb8aa3b, v13
	v_sub_f32_e32 v14, v77, v129
	v_add_f32_e32 v0, v8, v0
	v_cvt_pk_bf16_f32 v55, v15, v56
	v_exp_f32_e32 v13, v13
	v_mul_f32_e32 v14, 0x3fb8aa3b, v14
	v_sub_f32_e32 v15, v78, v129
	v_sub_f32_e32 v56, v79, v129
	v_add_f32_e32 v0, v9, v0
	v_exp_f32_e32 v14, v14
	v_mul_f32_e32 v15, 0x3fb8aa3b, v15
	v_mul_f32_e32 v56, 0x3fb8aa3b, v56
	v_add_f32_e32 v0, v10, v0
	v_exp_f32_e32 v15, v15
	v_exp_f32_e32 v64, v56
	v_cvt_pk_bf16_f32 v56, v1, v2
	v_add_f32_e32 v0, v11, v0
	v_sub_f32_e32 v1, v112, v129
	v_add_f32_e32 v0, v12, v0
	v_mul_f32_e32 v1, 0x3fb8aa3b, v1
	v_sub_f32_e32 v2, v113, v129
	v_cvt_pk_bf16_f32 v57, v3, v4
	v_add_f32_e32 v0, v13, v0
	v_exp_f32_e32 v1, v1
	v_mul_f32_e32 v2, 0x3fb8aa3b, v2
	v_sub_f32_e32 v3, v114, v129
	v_add_f32_e32 v0, v14, v0
	v_exp_f32_e32 v2, v2
	v_mul_f32_e32 v3, 0x3fb8aa3b, v3
	v_sub_f32_e32 v4, v115, v129
	v_cvt_pk_bf16_f32 v58, v5, v6
	v_add_f32_e32 v0, v15, v0
	v_exp_f32_e32 v3, v3
	v_mul_f32_e32 v4, 0x3fb8aa3b, v4
	v_sub_f32_e32 v5, v116, v129
	v_add_f32_e32 v0, v64, v0
	v_exp_f32_e32 v4, v4
	v_mul_f32_e32 v5, 0x3fb8aa3b, v5
	v_sub_f32_e32 v6, v117, v129
	v_cvt_pk_bf16_f32 v59, v7, v8
	v_exp_f32_e32 v5, v5
	v_mul_f32_e32 v6, 0x3fb8aa3b, v6
	v_sub_f32_e32 v7, v118, v129
	v_add_f32_e32 v0, v1, v0
	v_exp_f32_e32 v6, v6
	v_mul_f32_e32 v7, 0x3fb8aa3b, v7
	v_sub_f32_e32 v8, v119, v129
	v_add_f32_e32 v0, v2, v0
	v_cvt_pk_bf16_f32 v60, v9, v10
	v_exp_f32_e32 v7, v7
	v_mul_f32_e32 v8, 0x3fb8aa3b, v8
	v_sub_f32_e32 v9, v120, v129
	v_add_f32_e32 v0, v3, v0
	v_exp_f32_e32 v8, v8
	v_mul_f32_e32 v9, 0x3fb8aa3b, v9
	v_sub_f32_e32 v10, v121, v129
	v_add_f32_e32 v0, v4, v0
	v_cvt_pk_bf16_f32 v61, v11, v12
	v_exp_f32_e32 v9, v9
	v_mul_f32_e32 v10, 0x3fb8aa3b, v10
	v_sub_f32_e32 v11, v122, v129
	v_add_f32_e32 v0, v5, v0
	v_exp_f32_e32 v10, v10
	v_mul_f32_e32 v11, 0x3fb8aa3b, v11
	v_sub_f32_e32 v12, v123, v129
	v_add_f32_e32 v0, v6, v0
	v_cvt_pk_bf16_f32 v62, v13, v14
	v_exp_f32_e32 v11, v11
	v_mul_f32_e32 v12, 0x3fb8aa3b, v12
	v_sub_f32_e32 v13, v124, v129
	v_add_f32_e32 v0, v7, v0
	v_exp_f32_e32 v12, v12
	v_mul_f32_e32 v13, 0x3fb8aa3b, v13
	v_sub_f32_e32 v14, v125, v129
	v_add_f32_e32 v0, v8, v0
	v_cvt_pk_bf16_f32 v63, v15, v64
	v_exp_f32_e32 v13, v13
	v_mul_f32_e32 v14, 0x3fb8aa3b, v14
	v_sub_f32_e32 v15, v126, v129
	v_add_f32_e32 v0, v9, v0
	v_exp_f32_e32 v14, v14
	v_mul_f32_e32 v15, 0x3fb8aa3b, v15
	v_sub_f32_e32 v64, v127, v129
	v_add_f32_e32 v0, v10, v0
	v_exp_f32_e32 v15, v15
	v_mul_f32_e32 v64, 0x3fb8aa3b, v64
	v_add_f32_e32 v0, v11, v0
	v_exp_f32_e32 v72, v64
	v_add_f32_e32 v0, v12, v0
	v_add_f32_e32 v0, v13, v0
	v_add_f32_e32 v0, v14, v0
	v_add_f32_e32 v0, v15, v0
	v_add_f32_e32 v0, v72, v0
	v_cvt_pk_bf16_f32 v64, v1, v2
	ds_bpermute_b32 v1, v128, v0
	v_cvt_pk_bf16_f32 v65, v3, v4
	v_cvt_pk_bf16_f32 v66, v5, v6
	v_cvt_pk_bf16_f32 v71, v15, v72
	v_cvt_pk_bf16_f32 v97, v132, v133
	s_waitcnt lgkmcnt(0)
	v_add_f32_e32 v0, v0, v1
	v_div_scale_f32 v1, s[14:15], v0, v0, 1.0
	v_rcp_f32_e32 v2, v1
	v_cvt_pk_bf16_f32 v98, v134, v135
	v_cvt_pk_bf16_f32 v99, v136, v137
	v_cvt_pk_bf16_f32 v32, v105, v106
	v_fma_f32 v3, -v1, v2, 1.0
	v_fmac_f32_e32 v2, v3, v2
	v_div_scale_f32 v3, vcc, 1.0, v0, 1.0
	v_mul_f32_e32 v4, v3, v2
	v_fma_f32 v5, -v1, v4, v3
	v_fmac_f32_e32 v4, v5, v2
	v_fma_f32 v1, -v1, v4, v3
	v_div_fmas_f32 v1, v1, v2, v4
	v_div_fixup_f32 v72, v1, v0, 1.0
	v_add_u32_e32 v0, s6, v214
	v_ashrrev_i32_e32 v1, 31, v0
	v_lshlrev_b64 v[0:1], 11, v[0:1]
	v_lshl_add_u64 v[2:3], s[48:49], 0, v[188:189]
	v_lshl_add_u64 v[0:1], v[0:1], 0, s[4:5]
	v_lshl_add_u64 v[0:1], v[2:3], 0, v[0:1]
	s_mov_b64 s[4:5], 0xc000020
	v_cvt_pk_bf16_f32 v33, v107, v108
	v_cvt_pk_bf16_f32 v34, v109, v110
	v_cvt_pk_bf16_f32 v35, v111, v130
	v_cvt_pk_bf16_f32 v67, v7, v8
	v_cvt_pk_bf16_f32 v68, v9, v10
	v_cvt_pk_bf16_f32 v69, v11, v12
	v_cvt_pk_bf16_f32 v70, v13, v14
	v_mov_b32_e32 v73, v72
	v_lshl_add_u64 v[74:75], v[0:1], 0, s[4:5]
	v_lshlrev_b32_e32 v76, 1, v211
	s_mov_b32 s4, 0
